# GEMM main loops: the back-to-back s_setprio 0 / s_setprio 1 pairs in the middle of each 32-MFMA cluster deleted (priority stays raised through the cluster)
# speedup vs baseline: 1.0019x; 1.0019x over previous
.LBB0_1531:
	ds_read_b128 v[128:131], v172
	ds_read_b128 v[176:179], v172 offset:1024
	ds_read_b128 v[180:183], v172 offset:2048
	ds_read_b128 v[184:187], v172 offset:3072
	ds_read_b128 v[188:191], v173
	ds_read_b128 v[192:195], v173 offset:1024
	ds_read_b128 v[196:199], v173 offset:2048
	ds_read_b128 v[204:207], v173 offset:3072
	s_add_u32 s8, s6, 0xfffc0080
	s_addc_u32 s9, s7, -1
	s_cmp_eq_u32 s64, 12
	s_cselect_b32 s41, s31, s9
	s_cselect_b32 s40, s42, s8
	s_cselect_b32 s9, s29, s45
	s_cselect_b32 s8, s43, s44
	v_lshl_add_u64 v[156:157], s[6:7], 0, v[146:147]
	s_add_i32 m0, s55, 0xc000
	ds_read_b128 v[208:211], v174
	ds_read_b128 v[212:215], v174 offset:1024
	ds_read_b128 v[216:219], v174 offset:2048
	ds_read_b128 v[220:223], v174 offset:3072
	ds_read_b128 v[224:227], v174 offset:4096
	ds_read_b128 v[228:231], v174 offset:5120
	ds_read_b128 v[232:235], v174 offset:6144
	ds_read_b128 v[236:239], v174 offset:7168
	global_load_lds_dwordx4 v[156:157], off
	v_lshl_add_u64 v[156:157], s[6:7], 0, v[148:149]
	s_add_i32 m0, s55, 0xe000
	s_nop 0
	global_load_lds_dwordx4 v[156:157], off
	s_waitcnt vmcnt(8)
	s_waitcnt lgkmcnt(0)
	s_barrier
	s_setprio 1
	s_waitcnt lgkmcnt(0)
	v_mfma_f32_16x16x32_bf16 v[124:127], v[128:131], v[208:211], v[124:127]
	v_mfma_f32_16x16x32_bf16 v[120:123], v[180:183], v[208:211], v[120:123]
	v_mfma_f32_16x16x32_bf16 v[108:111], v[128:131], v[216:219], v[108:111]
	v_mfma_f32_16x16x32_bf16 v[104:107], v[180:183], v[216:219], v[104:107]
	v_mfma_f32_16x16x32_bf16 v[92:95], v[128:131], v[224:227], v[92:95]
	v_mfma_f32_16x16x32_bf16 v[88:91], v[180:183], v[224:227], v[88:91]
	v_mfma_f32_16x16x32_bf16 v[76:79], v[128:131], v[232:235], v[76:79]
	v_mfma_f32_16x16x32_bf16 v[72:75], v[180:183], v[232:235], v[72:75]
	v_mfma_f32_16x16x32_bf16 v[124:127], v[176:179], v[212:215], v[124:127]
	v_mfma_f32_16x16x32_bf16 v[120:123], v[184:187], v[212:215], v[120:123]
	v_mfma_f32_16x16x32_bf16 v[108:111], v[176:179], v[220:223], v[108:111]
	v_mfma_f32_16x16x32_bf16 v[104:107], v[184:187], v[220:223], v[104:107]
	v_mfma_f32_16x16x32_bf16 v[92:95], v[176:179], v[228:231], v[92:95]
	v_mfma_f32_16x16x32_bf16 v[88:91], v[184:187], v[228:231], v[88:91]
	v_mfma_f32_16x16x32_bf16 v[76:79], v[176:179], v[236:239], v[76:79]
	v_mfma_f32_16x16x32_bf16 v[72:75], v[184:187], v[236:239], v[72:75]
	v_mfma_f32_16x16x32_bf16 v[116:119], v[188:191], v[208:211], v[116:119]
	v_mfma_f32_16x16x32_bf16 v[112:115], v[196:199], v[208:211], v[112:115]
	v_mfma_f32_16x16x32_bf16 v[100:103], v[188:191], v[216:219], v[100:103]
	v_mfma_f32_16x16x32_bf16 v[96:99], v[196:199], v[216:219], v[96:99]
	v_mfma_f32_16x16x32_bf16 v[84:87], v[188:191], v[224:227], v[84:87]
	v_mfma_f32_16x16x32_bf16 v[80:83], v[196:199], v[224:227], v[80:83]
	v_mfma_f32_16x16x32_bf16 v[68:71], v[188:191], v[232:235], v[68:71]
	v_mfma_f32_16x16x32_bf16 v[64:67], v[196:199], v[232:235], v[64:67]
	v_mfma_f32_16x16x32_bf16 v[116:119], v[192:195], v[212:215], v[116:119]
	v_mfma_f32_16x16x32_bf16 v[112:115], v[204:207], v[212:215], v[112:115]
	v_mfma_f32_16x16x32_bf16 v[100:103], v[192:195], v[220:223], v[100:103]
	v_mfma_f32_16x16x32_bf16 v[96:99], v[204:207], v[220:223], v[96:99]
	v_mfma_f32_16x16x32_bf16 v[84:87], v[192:195], v[228:231], v[84:87]
	v_mfma_f32_16x16x32_bf16 v[80:83], v[204:207], v[228:231], v[80:83]
	v_mfma_f32_16x16x32_bf16 v[68:71], v[192:195], v[236:239], v[68:71]
	v_mfma_f32_16x16x32_bf16 v[64:67], v[204:207], v[236:239], v[64:67]
	s_setprio 0
	s_barrier
	s_add_i32 s65, s62, s54
	v_lshl_add_u64 v[156:157], s[8:9], 0, v[134:135]
	s_mov_b32 m0, s65
	ds_read_b128 v[208:211], v174 offset:16384
	ds_read_b128 v[212:215], v174 offset:17408
	ds_read_b128 v[216:219], v174 offset:18432
	ds_read_b128 v[220:223], v174 offset:19456
	ds_read_b128 v[224:227], v174 offset:20480
	ds_read_b128 v[228:231], v174 offset:21504
	ds_read_b128 v[232:235], v174 offset:22528
	ds_read_b128 v[236:239], v174 offset:23552
	global_load_lds_dwordx4 v[156:157], off
	s_add_i32 m0, s65, 0x2000
	s_add_u32 s66, s8, 0x40000
	v_lshl_add_u64 v[200:201], s[8:9], 0, v[138:139]
	s_addc_u32 s67, s9, 0
	s_add_i32 s65, s63, s54
	global_load_lds_dwordx4 v[200:201], off
	v_lshl_add_u64 v[240:241], s[66:67], 0, v[134:135]
	s_mov_b32 m0, s65
	v_lshl_add_u64 v[242:243], s[40:41], 0, v[136:137]
	global_load_lds_dwordx4 v[240:241], off
	v_lshl_add_u64 v[240:241], s[66:67], 0, v[138:139]
	s_add_i32 m0, s65, 0x2000
	s_nop 0
	global_load_lds_dwordx4 v[240:241], off
	v_lshl_add_u64 v[240:241], s[40:41], 0, v[132:133]
	s_mov_b32 m0, s55
	s_nop 0
	global_load_lds_dwordx4 v[240:241], off
	s_mov_b32 m0, s56
	s_nop 0
	global_load_lds_dwordx4 v[242:243], off
	s_waitcnt vmcnt(8)
	s_waitcnt lgkmcnt(0)
	s_barrier
	s_setprio 1
	s_waitcnt lgkmcnt(0)
	v_mfma_f32_16x16x32_bf16 v[60:63], v[128:131], v[208:211], v[60:63]
	v_mfma_f32_16x16x32_bf16 v[56:59], v[180:183], v[208:211], v[56:59]
	v_mfma_f32_16x16x32_bf16 v[44:47], v[128:131], v[216:219], v[44:47]
	v_mfma_f32_16x16x32_bf16 v[40:43], v[180:183], v[216:219], v[40:43]
	v_mfma_f32_16x16x32_bf16 v[28:31], v[128:131], v[224:227], v[28:31]
	v_mfma_f32_16x16x32_bf16 v[24:27], v[180:183], v[224:227], v[24:27]
	v_mfma_f32_16x16x32_bf16 v[12:15], v[128:131], v[232:235], v[12:15]
	v_mfma_f32_16x16x32_bf16 v[8:11], v[180:183], v[232:235], v[8:11]
	v_mfma_f32_16x16x32_bf16 v[60:63], v[176:179], v[212:215], v[60:63]
	v_mfma_f32_16x16x32_bf16 v[56:59], v[184:187], v[212:215], v[56:59]
	v_mfma_f32_16x16x32_bf16 v[44:47], v[176:179], v[220:223], v[44:47]
	v_mfma_f32_16x16x32_bf16 v[40:43], v[184:187], v[220:223], v[40:43]
	v_mfma_f32_16x16x32_bf16 v[28:31], v[176:179], v[228:231], v[28:31]
	v_mfma_f32_16x16x32_bf16 v[24:27], v[184:187], v[228:231], v[24:27]
	v_mfma_f32_16x16x32_bf16 v[12:15], v[176:179], v[236:239], v[12:15]
	v_mfma_f32_16x16x32_bf16 v[8:11], v[184:187], v[236:239], v[8:11]
	v_mfma_f32_16x16x32_bf16 v[52:55], v[188:191], v[208:211], v[52:55]
	v_mfma_f32_16x16x32_bf16 v[48:51], v[196:199], v[208:211], v[48:51]
	v_mfma_f32_16x16x32_bf16 v[36:39], v[188:191], v[216:219], v[36:39]
	v_mfma_f32_16x16x32_bf16 v[32:35], v[196:199], v[216:219], v[32:35]
	v_mfma_f32_16x16x32_bf16 v[20:23], v[188:191], v[224:227], v[20:23]
	v_mfma_f32_16x16x32_bf16 v[16:19], v[196:199], v[224:227], v[16:19]
	v_mfma_f32_16x16x32_bf16 v[4:7], v[188:191], v[232:235], v[4:7]
	v_mfma_f32_16x16x32_bf16 v[0:3], v[196:199], v[232:235], v[0:3]
	v_mfma_f32_16x16x32_bf16 v[52:55], v[192:195], v[212:215], v[52:55]
	v_mfma_f32_16x16x32_bf16 v[48:51], v[204:207], v[212:215], v[48:51]
	v_mfma_f32_16x16x32_bf16 v[36:39], v[192:195], v[220:223], v[36:39]
	v_mfma_f32_16x16x32_bf16 v[32:35], v[204:207], v[220:223], v[32:35]
	v_mfma_f32_16x16x32_bf16 v[20:23], v[192:195], v[228:231], v[20:23]
	v_mfma_f32_16x16x32_bf16 v[16:19], v[204:207], v[228:231], v[16:19]
	v_mfma_f32_16x16x32_bf16 v[4:7], v[192:195], v[236:239], v[4:7]
	v_mfma_f32_16x16x32_bf16 v[0:3], v[204:207], v[236:239], v[0:3]
	s_setprio 0
	s_barrier
	s_add_i32 s65, 0, 0x18000
	v_add_u32_e32 v144, s65, v164
	s_add_i32 s66, 0, 0x1c000
	ds_read_b128 v[128:131], v144
	ds_read_b128 v[176:179], v144 offset:1024
	ds_read_b128 v[180:183], v144 offset:2048
	ds_read_b128 v[184:187], v144 offset:3072
	v_add_u32_e32 v144, s66, v164
	ds_read_b128 v[188:191], v144
	ds_read_b128 v[192:195], v144 offset:1024
	ds_read_b128 v[196:199], v144 offset:2048
	ds_read_b128 v[204:207], v144 offset:3072
	s_add_u32 s40, s40, 0x40000
	s_addc_u32 s41, s41, 0
	s_mov_b32 m0, s57
	v_lshl_add_u64 v[244:245], s[40:41], 0, v[132:133]
	ds_read_b128 v[208:211], v174 offset:32768
	ds_read_b128 v[212:215], v174 offset:33792
	ds_read_b128 v[216:219], v174 offset:34816
	ds_read_b128 v[220:223], v174 offset:35840
	ds_read_b128 v[224:227], v174 offset:36864
	ds_read_b128 v[228:231], v174 offset:37888
	ds_read_b128 v[232:235], v174 offset:38912
	ds_read_b128 v[236:239], v174 offset:39936
	global_load_lds_dwordx4 v[244:245], off
	v_lshl_add_u64 v[244:245], s[40:41], 0, v[136:137]
	s_mov_b32 m0, s58
	s_nop 0
	global_load_lds_dwordx4 v[244:245], off
	s_waitcnt vmcnt(8)
	s_waitcnt lgkmcnt(0)
	s_barrier
	s_setprio 1
	s_waitcnt lgkmcnt(0)
	v_mfma_f32_16x16x32_bf16 v[124:127], v[128:131], v[208:211], v[124:127]
	v_mfma_f32_16x16x32_bf16 v[120:123], v[180:183], v[208:211], v[120:123]
	v_mfma_f32_16x16x32_bf16 v[108:111], v[128:131], v[216:219], v[108:111]
	v_mfma_f32_16x16x32_bf16 v[104:107], v[180:183], v[216:219], v[104:107]
	v_mfma_f32_16x16x32_bf16 v[92:95], v[128:131], v[224:227], v[92:95]
	v_mfma_f32_16x16x32_bf16 v[88:91], v[180:183], v[224:227], v[88:91]
	v_mfma_f32_16x16x32_bf16 v[76:79], v[128:131], v[232:235], v[76:79]
	v_mfma_f32_16x16x32_bf16 v[72:75], v[180:183], v[232:235], v[72:75]
	v_mfma_f32_16x16x32_bf16 v[124:127], v[176:179], v[212:215], v[124:127]
	v_mfma_f32_16x16x32_bf16 v[120:123], v[184:187], v[212:215], v[120:123]
	v_mfma_f32_16x16x32_bf16 v[108:111], v[176:179], v[220:223], v[108:111]
	v_mfma_f32_16x16x32_bf16 v[104:107], v[184:187], v[220:223], v[104:107]
	v_mfma_f32_16x16x32_bf16 v[92:95], v[176:179], v[228:231], v[92:95]
	v_mfma_f32_16x16x32_bf16 v[88:91], v[184:187], v[228:231], v[88:91]
	v_mfma_f32_16x16x32_bf16 v[76:79], v[176:179], v[236:239], v[76:79]
	v_mfma_f32_16x16x32_bf16 v[72:75], v[184:187], v[236:239], v[72:75]
	v_mfma_f32_16x16x32_bf16 v[116:119], v[188:191], v[208:211], v[116:119]
	v_mfma_f32_16x16x32_bf16 v[112:115], v[196:199], v[208:211], v[112:115]
	v_mfma_f32_16x16x32_bf16 v[100:103], v[188:191], v[216:219], v[100:103]
	v_mfma_f32_16x16x32_bf16 v[96:99], v[196:199], v[216:219], v[96:99]
	v_mfma_f32_16x16x32_bf16 v[84:87], v[188:191], v[224:227], v[84:87]
	v_mfma_f32_16x16x32_bf16 v[80:83], v[196:199], v[224:227], v[80:83]
	v_mfma_f32_16x16x32_bf16 v[68:71], v[188:191], v[232:235], v[68:71]
	v_mfma_f32_16x16x32_bf16 v[64:67], v[196:199], v[232:235], v[64:67]
	v_mfma_f32_16x16x32_bf16 v[116:119], v[192:195], v[212:215], v[116:119]
	v_mfma_f32_16x16x32_bf16 v[112:115], v[204:207], v[212:215], v[112:115]
	v_mfma_f32_16x16x32_bf16 v[100:103], v[192:195], v[220:223], v[100:103]
	v_mfma_f32_16x16x32_bf16 v[96:99], v[204:207], v[220:223], v[96:99]
	v_mfma_f32_16x16x32_bf16 v[84:87], v[192:195], v[228:231], v[84:87]
	v_mfma_f32_16x16x32_bf16 v[80:83], v[204:207], v[228:231], v[80:83]
	v_mfma_f32_16x16x32_bf16 v[68:71], v[192:195], v[236:239], v[68:71]
	v_mfma_f32_16x16x32_bf16 v[64:67], v[204:207], v[236:239], v[64:67]
	s_setprio 0
	s_barrier
	s_add_i32 s40, s65, s54
	v_lshl_add_u64 v[156:157], v[156:157], 0, s[22:23]
	s_mov_b32 m0, s40
	ds_read_b128 v[208:211], v174 offset:49152
	ds_read_b128 v[212:215], v174 offset:50176
	ds_read_b128 v[216:219], v174 offset:51200
	ds_read_b128 v[220:223], v174 offset:52224
	ds_read_b128 v[224:227], v174 offset:53248
	ds_read_b128 v[228:231], v174 offset:54272
	ds_read_b128 v[232:235], v174 offset:55296
	ds_read_b128 v[236:239], v174 offset:56320
	global_load_lds_dwordx4 v[156:157], off
	s_add_i32 m0, s40, 0x2000
	s_add_u32 s8, s8, 0x40080
	v_lshl_add_u64 v[156:157], v[200:201], 0, s[22:23]
	s_addc_u32 s9, s9, 0
	s_add_i32 s40, s66, s54
	global_load_lds_dwordx4 v[156:157], off
	v_lshl_add_u64 v[156:157], s[8:9], 0, v[134:135]
	s_mov_b32 m0, s40
	s_nop 0
	global_load_lds_dwordx4 v[156:157], off
	v_lshl_add_u64 v[156:157], s[8:9], 0, v[138:139]
	s_add_i32 m0, s40, 0x2000
	s_nop 0
	global_load_lds_dwordx4 v[156:157], off
	v_lshl_add_u64 v[156:157], v[240:241], 0, s[22:23]
	s_mov_b32 m0, s59
	s_nop 0
	global_load_lds_dwordx4 v[156:157], off
	v_lshl_add_u64 v[156:157], v[242:243], 0, s[22:23]
	s_mov_b32 m0, s60
	s_nop 0
	global_load_lds_dwordx4 v[156:157], off
	s_waitcnt vmcnt(8)
	s_waitcnt lgkmcnt(0)
	s_barrier
	s_setprio 1
	s_waitcnt lgkmcnt(0)
	v_mfma_f32_16x16x32_bf16 v[60:63], v[128:131], v[208:211], v[60:63]
	v_mfma_f32_16x16x32_bf16 v[56:59], v[180:183], v[208:211], v[56:59]
	v_mfma_f32_16x16x32_bf16 v[44:47], v[128:131], v[216:219], v[44:47]
	v_mfma_f32_16x16x32_bf16 v[40:43], v[180:183], v[216:219], v[40:43]
	v_mfma_f32_16x16x32_bf16 v[28:31], v[128:131], v[224:227], v[28:31]
	v_mfma_f32_16x16x32_bf16 v[24:27], v[180:183], v[224:227], v[24:27]
	v_mfma_f32_16x16x32_bf16 v[12:15], v[128:131], v[232:235], v[12:15]
	v_mfma_f32_16x16x32_bf16 v[8:11], v[180:183], v[232:235], v[8:11]
	v_mfma_f32_16x16x32_bf16 v[60:63], v[176:179], v[212:215], v[60:63]
	v_mfma_f32_16x16x32_bf16 v[56:59], v[184:187], v[212:215], v[56:59]
	v_mfma_f32_16x16x32_bf16 v[44:47], v[176:179], v[220:223], v[44:47]
	v_mfma_f32_16x16x32_bf16 v[40:43], v[184:187], v[220:223], v[40:43]
	v_mfma_f32_16x16x32_bf16 v[28:31], v[176:179], v[228:231], v[28:31]
	v_mfma_f32_16x16x32_bf16 v[24:27], v[184:187], v[228:231], v[24:27]
	v_mfma_f32_16x16x32_bf16 v[12:15], v[176:179], v[236:239], v[12:15]
	v_mfma_f32_16x16x32_bf16 v[8:11], v[184:187], v[236:239], v[8:11]
	v_mfma_f32_16x16x32_bf16 v[52:55], v[188:191], v[208:211], v[52:55]
	v_mfma_f32_16x16x32_bf16 v[48:51], v[196:199], v[208:211], v[48:51]
	v_mfma_f32_16x16x32_bf16 v[36:39], v[188:191], v[216:219], v[36:39]
	v_mfma_f32_16x16x32_bf16 v[32:35], v[196:199], v[216:219], v[32:35]
	v_mfma_f32_16x16x32_bf16 v[20:23], v[188:191], v[224:227], v[20:23]
	v_mfma_f32_16x16x32_bf16 v[16:19], v[196:199], v[224:227], v[16:19]
	v_mfma_f32_16x16x32_bf16 v[4:7], v[188:191], v[232:235], v[4:7]
	v_mfma_f32_16x16x32_bf16 v[0:3], v[196:199], v[232:235], v[0:3]
	v_mfma_f32_16x16x32_bf16 v[52:55], v[192:195], v[212:215], v[52:55]
	v_mfma_f32_16x16x32_bf16 v[48:51], v[204:207], v[212:215], v[48:51]
	v_mfma_f32_16x16x32_bf16 v[36:39], v[192:195], v[220:223], v[36:39]
	v_mfma_f32_16x16x32_bf16 v[32:35], v[204:207], v[220:223], v[32:35]
	v_mfma_f32_16x16x32_bf16 v[20:23], v[192:195], v[228:231], v[20:23]
	v_mfma_f32_16x16x32_bf16 v[16:19], v[204:207], v[228:231], v[16:19]
	v_mfma_f32_16x16x32_bf16 v[4:7], v[192:195], v[236:239], v[4:7]
	v_mfma_f32_16x16x32_bf16 v[0:3], v[204:207], v[236:239], v[0:3]
	s_setprio 0
	s_barrier
	s_add_i32 s64, s64, 2
	s_add_u32 s6, s6, 0x100
	s_addc_u32 s7, s7, 0
	s_add_u32 s44, s44, 0x100
	s_addc_u32 s45, s45, 0
	s_cmp_gt_u32 s64, 13
	s_cbranch_scc0 .LBB0_1531
	s_and_b64 vcc, exec, s[24:25]
	s_cbranch_vccz .LBB0_1534
	s_barrier

.LBB0_1665:
	ds_read_b128 v[154:157], v146
	ds_read_b128 v[164:167], v146 offset:1024
	ds_read_b128 v[168:171], v146 offset:2048
	ds_read_b128 v[172:175], v146 offset:3072
	ds_read_b128 v[176:179], v147
	ds_read_b128 v[180:183], v147 offset:1024
	ds_read_b128 v[184:187], v147 offset:2048
	ds_read_b128 v[188:191], v147 offset:3072
	s_add_u32 s24, s22, 0xfffc0080
	s_addc_u32 s25, s23, -1
	s_cmp_eq_u32 s53, 12
	s_cselect_b32 s27, s15, s25
	s_cselect_b32 s26, s49, s24
	s_cselect_b32 s25, s13, s52
	s_cselect_b32 s24, s50, s51
	v_lshl_add_u64 v[150:151], s[22:23], 0, v[130:131]
	s_add_i32 m0, s39, 0xc000
	ds_read_b128 v[192:195], v148
	ds_read_b128 v[196:199], v148 offset:1024
	ds_read_b128 v[204:207], v148 offset:2048
	ds_read_b128 v[208:211], v148 offset:3072
	ds_read_b128 v[212:215], v148 offset:4096
	ds_read_b128 v[216:219], v148 offset:5120
	ds_read_b128 v[220:223], v148 offset:6144
	ds_read_b128 v[224:227], v148 offset:7168
	global_load_lds_dwordx4 v[150:151], off
	v_lshl_add_u64 v[150:151], s[22:23], 0, v[142:143]
	s_add_i32 m0, s39, 0xe000
	s_nop 0
	global_load_lds_dwordx4 v[150:151], off
	s_waitcnt vmcnt(8)
	s_waitcnt lgkmcnt(0)
	s_barrier
	s_setprio 1
	s_waitcnt lgkmcnt(0)
	v_mfma_f32_16x16x32_bf16 v[124:127], v[154:157], v[192:195], v[124:127]
	v_mfma_f32_16x16x32_bf16 v[120:123], v[168:171], v[192:195], v[120:123]
	v_mfma_f32_16x16x32_bf16 v[116:119], v[154:157], v[204:207], v[116:119]
	v_mfma_f32_16x16x32_bf16 v[112:115], v[168:171], v[204:207], v[112:115]
	v_mfma_f32_16x16x32_bf16 v[100:103], v[154:157], v[212:215], v[100:103]
	v_mfma_f32_16x16x32_bf16 v[96:99], v[168:171], v[212:215], v[96:99]
	v_mfma_f32_16x16x32_bf16 v[84:87], v[154:157], v[220:223], v[84:87]
	v_mfma_f32_16x16x32_bf16 v[80:83], v[168:171], v[220:223], v[80:83]
	v_mfma_f32_16x16x32_bf16 v[124:127], v[164:167], v[196:199], v[124:127]
	v_mfma_f32_16x16x32_bf16 v[120:123], v[172:175], v[196:199], v[120:123]
	v_mfma_f32_16x16x32_bf16 v[116:119], v[164:167], v[208:211], v[116:119]
	v_mfma_f32_16x16x32_bf16 v[112:115], v[172:175], v[208:211], v[112:115]
	v_mfma_f32_16x16x32_bf16 v[100:103], v[164:167], v[216:219], v[100:103]
	v_mfma_f32_16x16x32_bf16 v[96:99], v[172:175], v[216:219], v[96:99]
	v_mfma_f32_16x16x32_bf16 v[84:87], v[164:167], v[224:227], v[84:87]
	v_mfma_f32_16x16x32_bf16 v[80:83], v[172:175], v[224:227], v[80:83]
	v_mfma_f32_16x16x32_bf16 v[108:111], v[176:179], v[192:195], v[108:111]
	v_mfma_f32_16x16x32_bf16 v[104:107], v[184:187], v[192:195], v[104:107]
	v_mfma_f32_16x16x32_bf16 v[92:95], v[176:179], v[204:207], v[92:95]
	v_mfma_f32_16x16x32_bf16 v[88:91], v[184:187], v[204:207], v[88:91]
	v_mfma_f32_16x16x32_bf16 v[76:79], v[176:179], v[212:215], v[76:79]
	v_mfma_f32_16x16x32_bf16 v[72:75], v[184:187], v[212:215], v[72:75]
	v_mfma_f32_16x16x32_bf16 v[68:71], v[176:179], v[220:223], v[68:71]
	v_mfma_f32_16x16x32_bf16 v[64:67], v[184:187], v[220:223], v[64:67]
	v_mfma_f32_16x16x32_bf16 v[108:111], v[180:183], v[196:199], v[108:111]
	v_mfma_f32_16x16x32_bf16 v[104:107], v[188:191], v[196:199], v[104:107]
	v_mfma_f32_16x16x32_bf16 v[92:95], v[180:183], v[208:211], v[92:95]
	v_mfma_f32_16x16x32_bf16 v[88:91], v[188:191], v[208:211], v[88:91]
	v_mfma_f32_16x16x32_bf16 v[76:79], v[180:183], v[216:219], v[76:79]
	v_mfma_f32_16x16x32_bf16 v[72:75], v[188:191], v[216:219], v[72:75]
	v_mfma_f32_16x16x32_bf16 v[68:71], v[180:183], v[224:227], v[68:71]
	v_mfma_f32_16x16x32_bf16 v[64:67], v[188:191], v[224:227], v[64:67]
	s_setprio 0
	s_barrier
	s_add_i32 s54, s47, s34
	v_lshl_add_u64 v[150:151], s[24:25], 0, v[134:135]
	s_mov_b32 m0, s54
	ds_read_b128 v[192:195], v148 offset:16384
	ds_read_b128 v[196:199], v148 offset:17408
	ds_read_b128 v[204:207], v148 offset:18432
	ds_read_b128 v[208:211], v148 offset:19456
	ds_read_b128 v[212:215], v148 offset:20480
	ds_read_b128 v[216:219], v148 offset:21504
	ds_read_b128 v[220:223], v148 offset:22528
	ds_read_b128 v[224:227], v148 offset:23552
	global_load_lds_dwordx4 v[150:151], off
	s_add_i32 m0, s54, 0x2000
	s_add_u32 s54, s24, 0x40000
	v_lshl_add_u64 v[200:201], s[24:25], 0, v[138:139]
	s_addc_u32 s55, s25, 0
	s_add_i32 s56, s48, s34
	global_load_lds_dwordx4 v[200:201], off
	v_lshl_add_u64 v[228:229], s[54:55], 0, v[134:135]
	s_mov_b32 m0, s56
	v_lshl_add_u64 v[230:231], s[26:27], 0, v[136:137]
	global_load_lds_dwordx4 v[228:229], off
	v_lshl_add_u64 v[228:229], s[54:55], 0, v[138:139]
	s_add_i32 m0, s56, 0x2000
	s_nop 0
	global_load_lds_dwordx4 v[228:229], off
	v_lshl_add_u64 v[228:229], s[26:27], 0, v[132:133]
	s_mov_b32 m0, s39
	s_nop 0
	global_load_lds_dwordx4 v[228:229], off
	s_mov_b32 m0, s40
	s_nop 0
	global_load_lds_dwordx4 v[230:231], off
	s_waitcnt vmcnt(8)
	s_waitcnt lgkmcnt(0)
	s_barrier
	s_setprio 1
	s_waitcnt lgkmcnt(0)
	v_mfma_f32_16x16x32_bf16 v[60:63], v[154:157], v[192:195], v[60:63]
	v_mfma_f32_16x16x32_bf16 v[56:59], v[168:171], v[192:195], v[56:59]
	v_mfma_f32_16x16x32_bf16 v[52:55], v[154:157], v[204:207], v[52:55]
	v_mfma_f32_16x16x32_bf16 v[48:51], v[168:171], v[204:207], v[48:51]
	v_mfma_f32_16x16x32_bf16 v[36:39], v[154:157], v[212:215], v[36:39]
	v_mfma_f32_16x16x32_bf16 v[32:35], v[168:171], v[212:215], v[32:35]
	v_mfma_f32_16x16x32_bf16 v[20:23], v[154:157], v[220:223], v[20:23]
	v_mfma_f32_16x16x32_bf16 v[16:19], v[168:171], v[220:223], v[16:19]
	v_mfma_f32_16x16x32_bf16 v[60:63], v[164:167], v[196:199], v[60:63]
	v_mfma_f32_16x16x32_bf16 v[56:59], v[172:175], v[196:199], v[56:59]
	v_mfma_f32_16x16x32_bf16 v[52:55], v[164:167], v[208:211], v[52:55]
	v_mfma_f32_16x16x32_bf16 v[48:51], v[172:175], v[208:211], v[48:51]
	v_mfma_f32_16x16x32_bf16 v[36:39], v[164:167], v[216:219], v[36:39]
	v_mfma_f32_16x16x32_bf16 v[32:35], v[172:175], v[216:219], v[32:35]
	v_mfma_f32_16x16x32_bf16 v[20:23], v[164:167], v[224:227], v[20:23]
	v_mfma_f32_16x16x32_bf16 v[16:19], v[172:175], v[224:227], v[16:19]
	v_mfma_f32_16x16x32_bf16 v[44:47], v[176:179], v[192:195], v[44:47]
	v_mfma_f32_16x16x32_bf16 v[40:43], v[184:187], v[192:195], v[40:43]
	v_mfma_f32_16x16x32_bf16 v[28:31], v[176:179], v[204:207], v[28:31]
	v_mfma_f32_16x16x32_bf16 v[24:27], v[184:187], v[204:207], v[24:27]
	v_mfma_f32_16x16x32_bf16 v[12:15], v[176:179], v[212:215], v[12:15]
	v_mfma_f32_16x16x32_bf16 v[8:11], v[184:187], v[212:215], v[8:11]
	v_mfma_f32_16x16x32_bf16 v[4:7], v[176:179], v[220:223], v[4:7]
	v_mfma_f32_16x16x32_bf16 v[0:3], v[184:187], v[220:223], v[0:3]
	v_mfma_f32_16x16x32_bf16 v[44:47], v[180:183], v[196:199], v[44:47]
	v_mfma_f32_16x16x32_bf16 v[40:43], v[188:191], v[196:199], v[40:43]
	v_mfma_f32_16x16x32_bf16 v[28:31], v[180:183], v[208:211], v[28:31]
	v_mfma_f32_16x16x32_bf16 v[24:27], v[188:191], v[208:211], v[24:27]
	v_mfma_f32_16x16x32_bf16 v[12:15], v[180:183], v[216:219], v[12:15]
	v_mfma_f32_16x16x32_bf16 v[8:11], v[188:191], v[216:219], v[8:11]
	v_mfma_f32_16x16x32_bf16 v[4:7], v[180:183], v[224:227], v[4:7]
	v_mfma_f32_16x16x32_bf16 v[0:3], v[188:191], v[224:227], v[0:3]
	s_setprio 0
	s_barrier
	s_add_i32 s54, 0, 0x18000
	v_add_u32_e32 v149, s54, v145
	s_add_i32 s55, 0, 0x1c000
	ds_read_b128 v[154:157], v149
	ds_read_b128 v[164:167], v149 offset:1024
	ds_read_b128 v[168:171], v149 offset:2048
	ds_read_b128 v[172:175], v149 offset:3072
	v_add_u32_e32 v149, s55, v145
	ds_read_b128 v[176:179], v149
	ds_read_b128 v[180:183], v149 offset:1024
	ds_read_b128 v[184:187], v149 offset:2048
	ds_read_b128 v[188:191], v149 offset:3072
	s_add_u32 s26, s26, 0x40000
	s_addc_u32 s27, s27, 0
	s_mov_b32 m0, s41
	v_lshl_add_u64 v[232:233], s[26:27], 0, v[132:133]
	ds_read_b128 v[192:195], v148 offset:32768
	ds_read_b128 v[196:199], v148 offset:33792
	ds_read_b128 v[204:207], v148 offset:34816
	ds_read_b128 v[208:211], v148 offset:35840
	ds_read_b128 v[212:215], v148 offset:36864
	ds_read_b128 v[216:219], v148 offset:37888
	ds_read_b128 v[220:223], v148 offset:38912
	ds_read_b128 v[224:227], v148 offset:39936
	global_load_lds_dwordx4 v[232:233], off
	v_lshl_add_u64 v[232:233], s[26:27], 0, v[136:137]
	s_mov_b32 m0, s42
	s_nop 0
	global_load_lds_dwordx4 v[232:233], off
	s_waitcnt vmcnt(8)
	s_waitcnt lgkmcnt(0)
	s_barrier
	s_setprio 1
	s_waitcnt lgkmcnt(0)
	v_mfma_f32_16x16x32_bf16 v[124:127], v[154:157], v[192:195], v[124:127]
	v_mfma_f32_16x16x32_bf16 v[120:123], v[168:171], v[192:195], v[120:123]
	v_mfma_f32_16x16x32_bf16 v[116:119], v[154:157], v[204:207], v[116:119]
	v_mfma_f32_16x16x32_bf16 v[112:115], v[168:171], v[204:207], v[112:115]
	v_mfma_f32_16x16x32_bf16 v[100:103], v[154:157], v[212:215], v[100:103]
	v_mfma_f32_16x16x32_bf16 v[96:99], v[168:171], v[212:215], v[96:99]
	v_mfma_f32_16x16x32_bf16 v[84:87], v[154:157], v[220:223], v[84:87]
	v_mfma_f32_16x16x32_bf16 v[80:83], v[168:171], v[220:223], v[80:83]
	v_mfma_f32_16x16x32_bf16 v[124:127], v[164:167], v[196:199], v[124:127]
	v_mfma_f32_16x16x32_bf16 v[120:123], v[172:175], v[196:199], v[120:123]
	v_mfma_f32_16x16x32_bf16 v[116:119], v[164:167], v[208:211], v[116:119]
	v_mfma_f32_16x16x32_bf16 v[112:115], v[172:175], v[208:211], v[112:115]
	v_mfma_f32_16x16x32_bf16 v[100:103], v[164:167], v[216:219], v[100:103]
	v_mfma_f32_16x16x32_bf16 v[96:99], v[172:175], v[216:219], v[96:99]
	v_mfma_f32_16x16x32_bf16 v[84:87], v[164:167], v[224:227], v[84:87]
	v_mfma_f32_16x16x32_bf16 v[80:83], v[172:175], v[224:227], v[80:83]
	v_mfma_f32_16x16x32_bf16 v[108:111], v[176:179], v[192:195], v[108:111]
	v_mfma_f32_16x16x32_bf16 v[104:107], v[184:187], v[192:195], v[104:107]
	v_mfma_f32_16x16x32_bf16 v[92:95], v[176:179], v[204:207], v[92:95]
	v_mfma_f32_16x16x32_bf16 v[88:91], v[184:187], v[204:207], v[88:91]
	v_mfma_f32_16x16x32_bf16 v[76:79], v[176:179], v[212:215], v[76:79]
	v_mfma_f32_16x16x32_bf16 v[72:75], v[184:187], v[212:215], v[72:75]
	v_mfma_f32_16x16x32_bf16 v[68:71], v[176:179], v[220:223], v[68:71]
	v_mfma_f32_16x16x32_bf16 v[64:67], v[184:187], v[220:223], v[64:67]
	v_mfma_f32_16x16x32_bf16 v[108:111], v[180:183], v[196:199], v[108:111]
	v_mfma_f32_16x16x32_bf16 v[104:107], v[188:191], v[196:199], v[104:107]
	v_mfma_f32_16x16x32_bf16 v[92:95], v[180:183], v[208:211], v[92:95]
	v_mfma_f32_16x16x32_bf16 v[88:91], v[188:191], v[208:211], v[88:91]
	v_mfma_f32_16x16x32_bf16 v[76:79], v[180:183], v[216:219], v[76:79]
	v_mfma_f32_16x16x32_bf16 v[72:75], v[188:191], v[216:219], v[72:75]
	v_mfma_f32_16x16x32_bf16 v[68:71], v[180:183], v[224:227], v[68:71]
	v_mfma_f32_16x16x32_bf16 v[64:67], v[188:191], v[224:227], v[64:67]
	s_setprio 0
	s_barrier
	s_add_i32 s26, s54, s34
	v_lshl_add_u64 v[150:151], v[150:151], 0, s[6:7]
	s_mov_b32 m0, s26
	ds_read_b128 v[192:195], v148 offset:49152
	ds_read_b128 v[196:199], v148 offset:50176
	ds_read_b128 v[204:207], v148 offset:51200
	ds_read_b128 v[208:211], v148 offset:52224
	ds_read_b128 v[212:215], v148 offset:53248
	ds_read_b128 v[216:219], v148 offset:54272
	ds_read_b128 v[220:223], v148 offset:55296
	ds_read_b128 v[224:227], v148 offset:56320
	global_load_lds_dwordx4 v[150:151], off
	s_add_i32 m0, s26, 0x2000
	s_add_u32 s24, s24, 0x40080
	v_lshl_add_u64 v[150:151], v[200:201], 0, s[6:7]
	s_addc_u32 s25, s25, 0
	s_add_i32 s26, s55, s34
	global_load_lds_dwordx4 v[150:151], off
	v_lshl_add_u64 v[150:151], s[24:25], 0, v[134:135]
	s_mov_b32 m0, s26
	s_nop 0
	global_load_lds_dwordx4 v[150:151], off
	v_lshl_add_u64 v[150:151], s[24:25], 0, v[138:139]
	s_add_i32 m0, s26, 0x2000
	s_nop 0
	global_load_lds_dwordx4 v[150:151], off
	v_lshl_add_u64 v[150:151], v[228:229], 0, s[6:7]
	s_mov_b32 m0, s44
	s_nop 0
	global_load_lds_dwordx4 v[150:151], off
	v_lshl_add_u64 v[150:151], v[230:231], 0, s[6:7]
	s_mov_b32 m0, s45
	s_nop 0
	global_load_lds_dwordx4 v[150:151], off
	s_waitcnt vmcnt(8)
	s_waitcnt lgkmcnt(0)
	s_barrier
	s_setprio 1
	s_waitcnt lgkmcnt(0)
	v_mfma_f32_16x16x32_bf16 v[60:63], v[154:157], v[192:195], v[60:63]
	v_mfma_f32_16x16x32_bf16 v[56:59], v[168:171], v[192:195], v[56:59]
	v_mfma_f32_16x16x32_bf16 v[52:55], v[154:157], v[204:207], v[52:55]
	v_mfma_f32_16x16x32_bf16 v[48:51], v[168:171], v[204:207], v[48:51]
	v_mfma_f32_16x16x32_bf16 v[36:39], v[154:157], v[212:215], v[36:39]
	v_mfma_f32_16x16x32_bf16 v[32:35], v[168:171], v[212:215], v[32:35]
	v_mfma_f32_16x16x32_bf16 v[20:23], v[154:157], v[220:223], v[20:23]
	v_mfma_f32_16x16x32_bf16 v[16:19], v[168:171], v[220:223], v[16:19]
	v_mfma_f32_16x16x32_bf16 v[60:63], v[164:167], v[196:199], v[60:63]
	v_mfma_f32_16x16x32_bf16 v[56:59], v[172:175], v[196:199], v[56:59]
	v_mfma_f32_16x16x32_bf16 v[52:55], v[164:167], v[208:211], v[52:55]
	v_mfma_f32_16x16x32_bf16 v[48:51], v[172:175], v[208:211], v[48:51]
	v_mfma_f32_16x16x32_bf16 v[36:39], v[164:167], v[216:219], v[36:39]
	v_mfma_f32_16x16x32_bf16 v[32:35], v[172:175], v[216:219], v[32:35]
	v_mfma_f32_16x16x32_bf16 v[20:23], v[164:167], v[224:227], v[20:23]
	v_mfma_f32_16x16x32_bf16 v[16:19], v[172:175], v[224:227], v[16:19]
	v_mfma_f32_16x16x32_bf16 v[44:47], v[176:179], v[192:195], v[44:47]
	v_mfma_f32_16x16x32_bf16 v[40:43], v[184:187], v[192:195], v[40:43]
	v_mfma_f32_16x16x32_bf16 v[28:31], v[176:179], v[204:207], v[28:31]
	v_mfma_f32_16x16x32_bf16 v[24:27], v[184:187], v[204:207], v[24:27]
	v_mfma_f32_16x16x32_bf16 v[12:15], v[176:179], v[212:215], v[12:15]
	v_mfma_f32_16x16x32_bf16 v[8:11], v[184:187], v[212:215], v[8:11]
	v_mfma_f32_16x16x32_bf16 v[4:7], v[176:179], v[220:223], v[4:7]
	v_mfma_f32_16x16x32_bf16 v[0:3], v[184:187], v[220:223], v[0:3]
	v_mfma_f32_16x16x32_bf16 v[44:47], v[180:183], v[196:199], v[44:47]
	v_mfma_f32_16x16x32_bf16 v[40:43], v[188:191], v[196:199], v[40:43]
	v_mfma_f32_16x16x32_bf16 v[28:31], v[180:183], v[208:211], v[28:31]
	v_mfma_f32_16x16x32_bf16 v[24:27], v[188:191], v[208:211], v[24:27]
	v_mfma_f32_16x16x32_bf16 v[12:15], v[180:183], v[216:219], v[12:15]
	v_mfma_f32_16x16x32_bf16 v[8:11], v[188:191], v[216:219], v[8:11]
	v_mfma_f32_16x16x32_bf16 v[4:7], v[180:183], v[224:227], v[4:7]
	v_mfma_f32_16x16x32_bf16 v[0:3], v[188:191], v[224:227], v[0:3]
	s_setprio 0
	s_barrier
	s_add_i32 s53, s53, 2
	s_add_u32 s22, s22, 0x100
	s_addc_u32 s23, s23, 0
	s_add_u32 s51, s51, 0x100
	s_addc_u32 s52, s52, 0
	s_cmp_gt_u32 s53, 13
	s_cbranch_scc0 .LBB0_1665
	v_readlane_b32 s52, v251, 8
	s_and_b64 vcc, exec, s[8:9]
	v_readlane_b32 s60, v251, 16
	v_readlane_b32 s61, v251, 17
	v_readlane_b32 s64, v251, 20
	v_readlane_b32 s65, v251, 21
	v_readlane_b32 s53, v251, 9
	v_readlane_b32 s54, v251, 10
	v_readlane_b32 s55, v251, 11
	v_readlane_b32 s56, v251, 12
	v_readlane_b32 s57, v251, 13
	v_readlane_b32 s58, v251, 14
	v_readlane_b32 s59, v251, 15
	v_readlane_b32 s62, v251, 18
	v_readlane_b32 s63, v251, 19
	v_readlane_b32 s66, v251, 22
	v_readlane_b32 s67, v251, 23
	s_cbranch_vccz .LBB0_1668
	s_barrier

.LBB0_1689:
	ds_read_b128 v[164:167], v160
	ds_read_b128 v[168:171], v160 offset:1024
	ds_read_b128 v[172:175], v160 offset:2048
	ds_read_b128 v[176:179], v160 offset:3072
	ds_read_b128 v[180:183], v163
	ds_read_b128 v[184:187], v163 offset:1024
	ds_read_b128 v[188:191], v163 offset:2048
	ds_read_b128 v[192:195], v163 offset:3072
	s_add_u32 s24, s22, 0xfffc0080
	s_addc_u32 s25, s23, -1
	s_cmp_eq_u32 s50, 12
	s_cselect_b32 s27, s17, s25
	s_cselect_b32 s26, s46, s24
	s_cselect_b32 s25, s15, s49
	s_cselect_b32 s24, s47, s48
	v_lshl_add_u64 v[200:201], s[22:23], 0, v[140:141]
	s_add_i32 m0, s39, 0xc000
	ds_read_b128 v[196:199], v161
	ds_read_b128 v[204:207], v161 offset:1024
	ds_read_b128 v[208:211], v161 offset:2048
	ds_read_b128 v[212:215], v161 offset:3072
	ds_read_b128 v[216:219], v161 offset:4096
	ds_read_b128 v[220:223], v161 offset:5120
	ds_read_b128 v[224:227], v161 offset:6144
	ds_read_b128 v[228:231], v161 offset:7168
	global_load_lds_dwordx4 v[200:201], off
	v_lshl_add_u64 v[200:201], s[22:23], 0, v[158:159]
	s_add_i32 m0, s39, 0xe000
	s_nop 0
	global_load_lds_dwordx4 v[200:201], off
	s_waitcnt vmcnt(8)
	s_waitcnt lgkmcnt(0)
	s_barrier
	s_setprio 1
	s_waitcnt lgkmcnt(0)
	v_mfma_f32_16x16x32_bf16 v[124:127], v[164:167], v[196:199], v[124:127]
	v_mfma_f32_16x16x32_bf16 v[120:123], v[172:175], v[196:199], v[120:123]
	v_mfma_f32_16x16x32_bf16 v[116:119], v[164:167], v[208:211], v[116:119]
	v_mfma_f32_16x16x32_bf16 v[112:115], v[172:175], v[208:211], v[112:115]
	v_mfma_f32_16x16x32_bf16 v[100:103], v[164:167], v[216:219], v[100:103]
	v_mfma_f32_16x16x32_bf16 v[96:99], v[172:175], v[216:219], v[96:99]
	v_mfma_f32_16x16x32_bf16 v[84:87], v[164:167], v[224:227], v[84:87]
	v_mfma_f32_16x16x32_bf16 v[80:83], v[172:175], v[224:227], v[80:83]
	v_mfma_f32_16x16x32_bf16 v[124:127], v[168:171], v[204:207], v[124:127]
	v_mfma_f32_16x16x32_bf16 v[120:123], v[176:179], v[204:207], v[120:123]
	v_mfma_f32_16x16x32_bf16 v[116:119], v[168:171], v[212:215], v[116:119]
	v_mfma_f32_16x16x32_bf16 v[112:115], v[176:179], v[212:215], v[112:115]
	v_mfma_f32_16x16x32_bf16 v[100:103], v[168:171], v[220:223], v[100:103]
	v_mfma_f32_16x16x32_bf16 v[96:99], v[176:179], v[220:223], v[96:99]
	v_mfma_f32_16x16x32_bf16 v[84:87], v[168:171], v[228:231], v[84:87]
	v_mfma_f32_16x16x32_bf16 v[80:83], v[176:179], v[228:231], v[80:83]
	v_mfma_f32_16x16x32_bf16 v[108:111], v[180:183], v[196:199], v[108:111]
	v_mfma_f32_16x16x32_bf16 v[104:107], v[188:191], v[196:199], v[104:107]
	v_mfma_f32_16x16x32_bf16 v[92:95], v[180:183], v[208:211], v[92:95]
	v_mfma_f32_16x16x32_bf16 v[88:91], v[188:191], v[208:211], v[88:91]
	v_mfma_f32_16x16x32_bf16 v[76:79], v[180:183], v[216:219], v[76:79]
	v_mfma_f32_16x16x32_bf16 v[72:75], v[188:191], v[216:219], v[72:75]
	v_mfma_f32_16x16x32_bf16 v[68:71], v[180:183], v[224:227], v[68:71]
	v_mfma_f32_16x16x32_bf16 v[64:67], v[188:191], v[224:227], v[64:67]
	v_mfma_f32_16x16x32_bf16 v[108:111], v[184:187], v[204:207], v[108:111]
	v_mfma_f32_16x16x32_bf16 v[104:107], v[192:195], v[204:207], v[104:107]
	v_mfma_f32_16x16x32_bf16 v[92:95], v[184:187], v[212:215], v[92:95]
	v_mfma_f32_16x16x32_bf16 v[88:91], v[192:195], v[212:215], v[88:91]
	v_mfma_f32_16x16x32_bf16 v[76:79], v[184:187], v[220:223], v[76:79]
	v_mfma_f32_16x16x32_bf16 v[72:75], v[192:195], v[220:223], v[72:75]
	v_mfma_f32_16x16x32_bf16 v[68:71], v[184:187], v[228:231], v[68:71]
	v_mfma_f32_16x16x32_bf16 v[64:67], v[192:195], v[228:231], v[64:67]
	s_setprio 0
	s_barrier
	s_add_i32 s51, s4, s34
	v_lshl_add_u64 v[200:201], s[24:25], 0, v[134:135]
	s_mov_b32 m0, s51
	ds_read_b128 v[196:199], v161 offset:16384
	ds_read_b128 v[204:207], v161 offset:17408
	ds_read_b128 v[208:211], v161 offset:18432
	ds_read_b128 v[212:215], v161 offset:19456
	ds_read_b128 v[216:219], v161 offset:20480
	ds_read_b128 v[220:223], v161 offset:21504
	ds_read_b128 v[224:227], v161 offset:22528
	ds_read_b128 v[228:231], v161 offset:23552
	global_load_lds_dwordx4 v[200:201], off
	s_add_i32 m0, s51, 0x2000
	s_add_u32 s52, s24, 0x40000
	v_lshl_add_u64 v[232:233], s[24:25], 0, v[138:139]
	s_addc_u32 s53, s25, 0
	s_add_i32 s51, s45, s34
	global_load_lds_dwordx4 v[232:233], off
	v_lshl_add_u64 v[234:235], s[52:53], 0, v[134:135]
	s_mov_b32 m0, s51
	v_lshl_add_u64 v[236:237], s[26:27], 0, v[136:137]
	global_load_lds_dwordx4 v[234:235], off
	v_lshl_add_u64 v[234:235], s[52:53], 0, v[138:139]
	s_add_i32 m0, s51, 0x2000
	s_nop 0
	global_load_lds_dwordx4 v[234:235], off
	v_lshl_add_u64 v[234:235], s[26:27], 0, v[132:133]
	s_mov_b32 m0, s39
	s_nop 0
	global_load_lds_dwordx4 v[234:235], off
	s_mov_b32 m0, s40
	s_nop 0
	global_load_lds_dwordx4 v[236:237], off
	s_waitcnt vmcnt(8)
	s_waitcnt lgkmcnt(0)
	s_barrier
	s_setprio 1
	s_waitcnt lgkmcnt(0)
	v_mfma_f32_16x16x32_bf16 v[60:63], v[164:167], v[196:199], v[60:63]
	v_mfma_f32_16x16x32_bf16 v[56:59], v[172:175], v[196:199], v[56:59]
	v_mfma_f32_16x16x32_bf16 v[52:55], v[164:167], v[208:211], v[52:55]
	v_mfma_f32_16x16x32_bf16 v[48:51], v[172:175], v[208:211], v[48:51]
	v_mfma_f32_16x16x32_bf16 v[36:39], v[164:167], v[216:219], v[36:39]
	v_mfma_f32_16x16x32_bf16 v[32:35], v[172:175], v[216:219], v[32:35]
	v_mfma_f32_16x16x32_bf16 v[20:23], v[164:167], v[224:227], v[20:23]
	v_mfma_f32_16x16x32_bf16 v[16:19], v[172:175], v[224:227], v[16:19]
	v_mfma_f32_16x16x32_bf16 v[60:63], v[168:171], v[204:207], v[60:63]
	v_mfma_f32_16x16x32_bf16 v[56:59], v[176:179], v[204:207], v[56:59]
	v_mfma_f32_16x16x32_bf16 v[52:55], v[168:171], v[212:215], v[52:55]
	v_mfma_f32_16x16x32_bf16 v[48:51], v[176:179], v[212:215], v[48:51]
	v_mfma_f32_16x16x32_bf16 v[36:39], v[168:171], v[220:223], v[36:39]
	v_mfma_f32_16x16x32_bf16 v[32:35], v[176:179], v[220:223], v[32:35]
	v_mfma_f32_16x16x32_bf16 v[20:23], v[168:171], v[228:231], v[20:23]
	v_mfma_f32_16x16x32_bf16 v[16:19], v[176:179], v[228:231], v[16:19]
	v_mfma_f32_16x16x32_bf16 v[44:47], v[180:183], v[196:199], v[44:47]
	v_mfma_f32_16x16x32_bf16 v[40:43], v[188:191], v[196:199], v[40:43]
	v_mfma_f32_16x16x32_bf16 v[28:31], v[180:183], v[208:211], v[28:31]
	v_mfma_f32_16x16x32_bf16 v[24:27], v[188:191], v[208:211], v[24:27]
	v_mfma_f32_16x16x32_bf16 v[12:15], v[180:183], v[216:219], v[12:15]
	v_mfma_f32_16x16x32_bf16 v[8:11], v[188:191], v[216:219], v[8:11]
	v_mfma_f32_16x16x32_bf16 v[4:7], v[180:183], v[224:227], v[4:7]
	v_mfma_f32_16x16x32_bf16 v[0:3], v[188:191], v[224:227], v[0:3]
	v_mfma_f32_16x16x32_bf16 v[44:47], v[184:187], v[204:207], v[44:47]
	v_mfma_f32_16x16x32_bf16 v[40:43], v[192:195], v[204:207], v[40:43]
	v_mfma_f32_16x16x32_bf16 v[28:31], v[184:187], v[212:215], v[28:31]
	v_mfma_f32_16x16x32_bf16 v[24:27], v[192:195], v[212:215], v[24:27]
	v_mfma_f32_16x16x32_bf16 v[12:15], v[184:187], v[220:223], v[12:15]
	v_mfma_f32_16x16x32_bf16 v[8:11], v[192:195], v[220:223], v[8:11]
	v_mfma_f32_16x16x32_bf16 v[4:7], v[184:187], v[228:231], v[4:7]
	v_mfma_f32_16x16x32_bf16 v[0:3], v[192:195], v[228:231], v[0:3]
	s_setprio 0
	s_barrier
	s_add_i32 s51, 0, 0x18000
	s_add_i32 s52, 0, 0x1c000
	v_add_u32_e32 v176, s51, v162
	v_add_u32_e32 v192, s52, v162
	ds_read_b128 v[164:167], v176
	ds_read_b128 v[168:171], v176 offset:1024
	ds_read_b128 v[172:175], v176 offset:2048
	ds_read_b128 v[176:179], v176 offset:3072
	ds_read_b128 v[180:183], v192
	ds_read_b128 v[184:187], v192 offset:1024
	ds_read_b128 v[188:191], v192 offset:2048
	ds_read_b128 v[192:195], v192 offset:3072
	s_add_u32 s26, s26, 0x40000
	s_addc_u32 s27, s27, 0
	s_mov_b32 m0, s41
	v_lshl_add_u64 v[238:239], s[26:27], 0, v[132:133]
	ds_read_b128 v[196:199], v161 offset:32768
	ds_read_b128 v[204:207], v161 offset:33792
	ds_read_b128 v[208:211], v161 offset:34816
	ds_read_b128 v[212:215], v161 offset:35840
	ds_read_b128 v[216:219], v161 offset:36864
	ds_read_b128 v[220:223], v161 offset:37888
	ds_read_b128 v[224:227], v161 offset:38912
	ds_read_b128 v[228:231], v161 offset:39936
	global_load_lds_dwordx4 v[238:239], off
	v_lshl_add_u64 v[238:239], s[26:27], 0, v[136:137]
	s_mov_b32 m0, s42
	s_nop 0
	global_load_lds_dwordx4 v[238:239], off
	s_waitcnt vmcnt(8)
	s_waitcnt lgkmcnt(0)
	s_barrier
	s_setprio 1
	s_waitcnt lgkmcnt(0)
	v_mfma_f32_16x16x32_bf16 v[124:127], v[164:167], v[196:199], v[124:127]
	v_mfma_f32_16x16x32_bf16 v[120:123], v[172:175], v[196:199], v[120:123]
	v_mfma_f32_16x16x32_bf16 v[116:119], v[164:167], v[208:211], v[116:119]
	v_mfma_f32_16x16x32_bf16 v[112:115], v[172:175], v[208:211], v[112:115]
	v_mfma_f32_16x16x32_bf16 v[100:103], v[164:167], v[216:219], v[100:103]
	v_mfma_f32_16x16x32_bf16 v[96:99], v[172:175], v[216:219], v[96:99]
	v_mfma_f32_16x16x32_bf16 v[84:87], v[164:167], v[224:227], v[84:87]
	v_mfma_f32_16x16x32_bf16 v[80:83], v[172:175], v[224:227], v[80:83]
	v_mfma_f32_16x16x32_bf16 v[124:127], v[168:171], v[204:207], v[124:127]
	v_mfma_f32_16x16x32_bf16 v[120:123], v[176:179], v[204:207], v[120:123]
	v_mfma_f32_16x16x32_bf16 v[116:119], v[168:171], v[212:215], v[116:119]
	v_mfma_f32_16x16x32_bf16 v[112:115], v[176:179], v[212:215], v[112:115]
	v_mfma_f32_16x16x32_bf16 v[100:103], v[168:171], v[220:223], v[100:103]
	v_mfma_f32_16x16x32_bf16 v[96:99], v[176:179], v[220:223], v[96:99]
	v_mfma_f32_16x16x32_bf16 v[84:87], v[168:171], v[228:231], v[84:87]
	v_mfma_f32_16x16x32_bf16 v[80:83], v[176:179], v[228:231], v[80:83]
	v_mfma_f32_16x16x32_bf16 v[108:111], v[180:183], v[196:199], v[108:111]
	v_mfma_f32_16x16x32_bf16 v[104:107], v[188:191], v[196:199], v[104:107]
	v_mfma_f32_16x16x32_bf16 v[92:95], v[180:183], v[208:211], v[92:95]
	v_mfma_f32_16x16x32_bf16 v[88:91], v[188:191], v[208:211], v[88:91]
	v_mfma_f32_16x16x32_bf16 v[76:79], v[180:183], v[216:219], v[76:79]
	v_mfma_f32_16x16x32_bf16 v[72:75], v[188:191], v[216:219], v[72:75]
	v_mfma_f32_16x16x32_bf16 v[68:71], v[180:183], v[224:227], v[68:71]
	v_mfma_f32_16x16x32_bf16 v[64:67], v[188:191], v[224:227], v[64:67]
	v_mfma_f32_16x16x32_bf16 v[108:111], v[184:187], v[204:207], v[108:111]
	v_mfma_f32_16x16x32_bf16 v[104:107], v[192:195], v[204:207], v[104:107]
	v_mfma_f32_16x16x32_bf16 v[92:95], v[184:187], v[212:215], v[92:95]
	v_mfma_f32_16x16x32_bf16 v[88:91], v[192:195], v[212:215], v[88:91]
	v_mfma_f32_16x16x32_bf16 v[76:79], v[184:187], v[220:223], v[76:79]
	v_mfma_f32_16x16x32_bf16 v[72:75], v[192:195], v[220:223], v[72:75]
	v_mfma_f32_16x16x32_bf16 v[68:71], v[184:187], v[228:231], v[68:71]
	v_mfma_f32_16x16x32_bf16 v[64:67], v[192:195], v[228:231], v[64:67]
	s_setprio 0
	s_barrier
	s_add_i32 s26, s51, s34
	v_lshl_add_u64 v[200:201], v[200:201], 0, s[6:7]
	s_mov_b32 m0, s26
	ds_read_b128 v[196:199], v161 offset:49152
	ds_read_b128 v[204:207], v161 offset:50176
	ds_read_b128 v[208:211], v161 offset:51200
	ds_read_b128 v[212:215], v161 offset:52224
	ds_read_b128 v[216:219], v161 offset:53248
	ds_read_b128 v[220:223], v161 offset:54272
	ds_read_b128 v[224:227], v161 offset:55296
	ds_read_b128 v[228:231], v161 offset:56320
	global_load_lds_dwordx4 v[200:201], off
	s_add_i32 m0, s26, 0x2000
	s_add_u32 s24, s24, 0x40080
	v_lshl_add_u64 v[200:201], v[232:233], 0, s[6:7]
	s_addc_u32 s25, s25, 0
	s_add_i32 s26, s52, s34
	global_load_lds_dwordx4 v[200:201], off
	v_lshl_add_u64 v[200:201], s[24:25], 0, v[134:135]
	s_mov_b32 m0, s26
	s_nop 0
	global_load_lds_dwordx4 v[200:201], off
	v_lshl_add_u64 v[200:201], s[24:25], 0, v[138:139]
	s_add_i32 m0, s26, 0x2000
	s_nop 0
	global_load_lds_dwordx4 v[200:201], off
	v_lshl_add_u64 v[200:201], v[234:235], 0, s[6:7]
	s_mov_b32 m0, s43
	s_nop 0
	global_load_lds_dwordx4 v[200:201], off
	v_lshl_add_u64 v[200:201], v[236:237], 0, s[6:7]
	s_mov_b32 m0, s44
	s_nop 0
	global_load_lds_dwordx4 v[200:201], off
	s_waitcnt vmcnt(8)
	s_waitcnt lgkmcnt(0)
	s_barrier
	s_setprio 1
	s_waitcnt lgkmcnt(0)
	v_mfma_f32_16x16x32_bf16 v[60:63], v[164:167], v[196:199], v[60:63]
	v_mfma_f32_16x16x32_bf16 v[56:59], v[172:175], v[196:199], v[56:59]
	v_mfma_f32_16x16x32_bf16 v[52:55], v[164:167], v[208:211], v[52:55]
	v_mfma_f32_16x16x32_bf16 v[48:51], v[172:175], v[208:211], v[48:51]
	v_mfma_f32_16x16x32_bf16 v[36:39], v[164:167], v[216:219], v[36:39]
	v_mfma_f32_16x16x32_bf16 v[32:35], v[172:175], v[216:219], v[32:35]
	v_mfma_f32_16x16x32_bf16 v[20:23], v[164:167], v[224:227], v[20:23]
	v_mfma_f32_16x16x32_bf16 v[16:19], v[172:175], v[224:227], v[16:19]
	v_mfma_f32_16x16x32_bf16 v[60:63], v[168:171], v[204:207], v[60:63]
	v_mfma_f32_16x16x32_bf16 v[56:59], v[176:179], v[204:207], v[56:59]
	v_mfma_f32_16x16x32_bf16 v[52:55], v[168:171], v[212:215], v[52:55]
	v_mfma_f32_16x16x32_bf16 v[48:51], v[176:179], v[212:215], v[48:51]
	v_mfma_f32_16x16x32_bf16 v[36:39], v[168:171], v[220:223], v[36:39]
	v_mfma_f32_16x16x32_bf16 v[32:35], v[176:179], v[220:223], v[32:35]
	v_mfma_f32_16x16x32_bf16 v[20:23], v[168:171], v[228:231], v[20:23]
	v_mfma_f32_16x16x32_bf16 v[16:19], v[176:179], v[228:231], v[16:19]
	v_mfma_f32_16x16x32_bf16 v[44:47], v[180:183], v[196:199], v[44:47]
	v_mfma_f32_16x16x32_bf16 v[40:43], v[188:191], v[196:199], v[40:43]
	v_mfma_f32_16x16x32_bf16 v[28:31], v[180:183], v[208:211], v[28:31]
	v_mfma_f32_16x16x32_bf16 v[24:27], v[188:191], v[208:211], v[24:27]
	v_mfma_f32_16x16x32_bf16 v[12:15], v[180:183], v[216:219], v[12:15]
	v_mfma_f32_16x16x32_bf16 v[8:11], v[188:191], v[216:219], v[8:11]
	v_mfma_f32_16x16x32_bf16 v[4:7], v[180:183], v[224:227], v[4:7]
	v_mfma_f32_16x16x32_bf16 v[0:3], v[188:191], v[224:227], v[0:3]
	v_mfma_f32_16x16x32_bf16 v[44:47], v[184:187], v[204:207], v[44:47]
	v_mfma_f32_16x16x32_bf16 v[40:43], v[192:195], v[204:207], v[40:43]
	v_mfma_f32_16x16x32_bf16 v[28:31], v[184:187], v[212:215], v[28:31]
	v_mfma_f32_16x16x32_bf16 v[24:27], v[192:195], v[212:215], v[24:27]
	v_mfma_f32_16x16x32_bf16 v[12:15], v[184:187], v[220:223], v[12:15]
	v_mfma_f32_16x16x32_bf16 v[8:11], v[192:195], v[220:223], v[8:11]
	v_mfma_f32_16x16x32_bf16 v[4:7], v[184:187], v[228:231], v[4:7]
	v_mfma_f32_16x16x32_bf16 v[0:3], v[192:195], v[228:231], v[0:3]
	s_setprio 0
	s_barrier
	s_add_i32 s50, s50, 2
	s_add_u32 s22, s22, 0x100
	s_addc_u32 s23, s23, 0
	s_add_u32 s48, s48, 0x100
	s_addc_u32 s49, s49, 0
	s_cmp_gt_u32 s50, 13
	s_cbranch_scc0 .LBB0_1689
	s_and_b64 vcc, exec, s[8:9]
	s_cbranch_vccz .LBB0_1692
	s_barrier

.LBB0_2238:
	ds_read_b128 v[144:147], v161
	ds_read_b128 v[164:167], v161 offset:1024
	ds_read_b128 v[168:171], v161 offset:2048
	ds_read_b128 v[172:175], v161 offset:3072
	ds_read_b128 v[176:179], v162
	ds_read_b128 v[180:183], v162 offset:1024
	ds_read_b128 v[184:187], v162 offset:2048
	ds_read_b128 v[188:191], v162 offset:3072
	s_add_u32 s30, s28, 0xfffe0080
	s_addc_u32 s31, s29, -1
	s_cmp_eq_u32 s59, 4
	s_cselect_b32 s35, s21, s31
	s_cselect_b32 s34, s55, s30
	s_cselect_b32 s31, s19, s58
	s_cselect_b32 s30, s56, s57
	v_lshl_add_u64 v[200:201], s[28:29], 0, v[136:137]
	s_add_i32 m0, s27, 0xc000
	ds_read_b128 v[192:195], v163
	ds_read_b128 v[196:199], v163 offset:1024
	ds_read_b128 v[204:207], v163 offset:2048
	ds_read_b128 v[208:211], v163 offset:3072
	ds_read_b128 v[212:215], v163 offset:4096
	ds_read_b128 v[216:219], v163 offset:5120
	ds_read_b128 v[220:223], v163 offset:6144
	ds_read_b128 v[224:227], v163 offset:7168
	global_load_lds_dwordx4 v[200:201], off
	v_lshl_add_u64 v[200:201], s[28:29], 0, v[138:139]
	s_add_i32 m0, s27, 0xe000
	s_nop 0
	global_load_lds_dwordx4 v[200:201], off
	s_waitcnt vmcnt(8)
	s_waitcnt lgkmcnt(0)
	s_barrier
	s_setprio 1
	s_waitcnt lgkmcnt(0)
	v_mfma_f32_16x16x32_bf16 v[124:127], v[144:147], v[192:195], v[124:127]
	v_mfma_f32_16x16x32_bf16 v[120:123], v[168:171], v[192:195], v[120:123]
	v_mfma_f32_16x16x32_bf16 v[108:111], v[144:147], v[204:207], v[108:111]
	v_mfma_f32_16x16x32_bf16 v[104:107], v[168:171], v[204:207], v[104:107]
	v_mfma_f32_16x16x32_bf16 v[92:95], v[144:147], v[212:215], v[92:95]
	v_mfma_f32_16x16x32_bf16 v[88:91], v[168:171], v[212:215], v[88:91]
	v_mfma_f32_16x16x32_bf16 v[76:79], v[144:147], v[220:223], v[76:79]
	v_mfma_f32_16x16x32_bf16 v[72:75], v[168:171], v[220:223], v[72:75]
	v_mfma_f32_16x16x32_bf16 v[124:127], v[164:167], v[196:199], v[124:127]
	v_mfma_f32_16x16x32_bf16 v[120:123], v[172:175], v[196:199], v[120:123]
	v_mfma_f32_16x16x32_bf16 v[108:111], v[164:167], v[208:211], v[108:111]
	v_mfma_f32_16x16x32_bf16 v[104:107], v[172:175], v[208:211], v[104:107]
	v_mfma_f32_16x16x32_bf16 v[92:95], v[164:167], v[216:219], v[92:95]
	v_mfma_f32_16x16x32_bf16 v[88:91], v[172:175], v[216:219], v[88:91]
	v_mfma_f32_16x16x32_bf16 v[76:79], v[164:167], v[224:227], v[76:79]
	v_mfma_f32_16x16x32_bf16 v[72:75], v[172:175], v[224:227], v[72:75]
	v_mfma_f32_16x16x32_bf16 v[116:119], v[176:179], v[192:195], v[116:119]
	v_mfma_f32_16x16x32_bf16 v[112:115], v[184:187], v[192:195], v[112:115]
	v_mfma_f32_16x16x32_bf16 v[100:103], v[176:179], v[204:207], v[100:103]
	v_mfma_f32_16x16x32_bf16 v[96:99], v[184:187], v[204:207], v[96:99]
	v_mfma_f32_16x16x32_bf16 v[84:87], v[176:179], v[212:215], v[84:87]
	v_mfma_f32_16x16x32_bf16 v[80:83], v[184:187], v[212:215], v[80:83]
	v_mfma_f32_16x16x32_bf16 v[68:71], v[176:179], v[220:223], v[68:71]
	v_mfma_f32_16x16x32_bf16 v[64:67], v[184:187], v[220:223], v[64:67]
	v_mfma_f32_16x16x32_bf16 v[116:119], v[180:183], v[196:199], v[116:119]
	v_mfma_f32_16x16x32_bf16 v[112:115], v[188:191], v[196:199], v[112:115]
	v_mfma_f32_16x16x32_bf16 v[100:103], v[180:183], v[208:211], v[100:103]
	v_mfma_f32_16x16x32_bf16 v[96:99], v[188:191], v[208:211], v[96:99]
	v_mfma_f32_16x16x32_bf16 v[84:87], v[180:183], v[216:219], v[84:87]
	v_mfma_f32_16x16x32_bf16 v[80:83], v[188:191], v[216:219], v[80:83]
	v_mfma_f32_16x16x32_bf16 v[68:71], v[180:183], v[224:227], v[68:71]
	v_mfma_f32_16x16x32_bf16 v[64:67], v[188:191], v[224:227], v[64:67]
	s_setprio 0
	s_barrier
	s_add_i32 s60, s52, s45
	v_lshl_add_u64 v[200:201], s[30:31], 0, v[130:131]
	s_mov_b32 m0, s60
	ds_read_b128 v[192:195], v163 offset:16384
	ds_read_b128 v[196:199], v163 offset:17408
	ds_read_b128 v[204:207], v163 offset:18432
	ds_read_b128 v[208:211], v163 offset:19456
	ds_read_b128 v[212:215], v163 offset:20480
	ds_read_b128 v[216:219], v163 offset:21504
	ds_read_b128 v[220:223], v163 offset:22528
	ds_read_b128 v[224:227], v163 offset:23552
	global_load_lds_dwordx4 v[200:201], off
	s_add_i32 m0, s60, 0x2000
	s_add_u32 s60, s30, 0x20000
	v_lshl_add_u64 v[228:229], s[30:31], 0, v[134:135]
	s_addc_u32 s61, s31, 0
	s_add_i32 s62, s53, s45
	global_load_lds_dwordx4 v[228:229], off
	v_lshl_add_u64 v[230:231], s[60:61], 0, v[130:131]
	s_mov_b32 m0, s62
	v_lshl_add_u64 v[232:233], s[34:35], 0, v[132:133]
	global_load_lds_dwordx4 v[230:231], off
	v_lshl_add_u64 v[230:231], s[60:61], 0, v[134:135]
	s_add_i32 m0, s62, 0x2000
	s_nop 0
	global_load_lds_dwordx4 v[230:231], off
	v_lshl_add_u64 v[230:231], s[34:35], 0, v[128:129]
	s_mov_b32 m0, s27
	s_nop 0
	global_load_lds_dwordx4 v[230:231], off
	s_mov_b32 m0, s46
	s_nop 0
	global_load_lds_dwordx4 v[232:233], off
	s_waitcnt vmcnt(8)
	s_waitcnt lgkmcnt(0)
	s_barrier
	s_setprio 1
	s_waitcnt lgkmcnt(0)
	v_mfma_f32_16x16x32_bf16 v[60:63], v[144:147], v[192:195], v[60:63]
	v_mfma_f32_16x16x32_bf16 v[56:59], v[168:171], v[192:195], v[56:59]
	v_mfma_f32_16x16x32_bf16 v[44:47], v[144:147], v[204:207], v[44:47]
	v_mfma_f32_16x16x32_bf16 v[40:43], v[168:171], v[204:207], v[40:43]
	v_mfma_f32_16x16x32_bf16 v[28:31], v[144:147], v[212:215], v[28:31]
	v_mfma_f32_16x16x32_bf16 v[24:27], v[168:171], v[212:215], v[24:27]
	v_mfma_f32_16x16x32_bf16 v[12:15], v[144:147], v[220:223], v[12:15]
	v_mfma_f32_16x16x32_bf16 v[8:11], v[168:171], v[220:223], v[8:11]
	v_mfma_f32_16x16x32_bf16 v[60:63], v[164:167], v[196:199], v[60:63]
	v_mfma_f32_16x16x32_bf16 v[56:59], v[172:175], v[196:199], v[56:59]
	v_mfma_f32_16x16x32_bf16 v[44:47], v[164:167], v[208:211], v[44:47]
	v_mfma_f32_16x16x32_bf16 v[40:43], v[172:175], v[208:211], v[40:43]
	v_mfma_f32_16x16x32_bf16 v[28:31], v[164:167], v[216:219], v[28:31]
	v_mfma_f32_16x16x32_bf16 v[24:27], v[172:175], v[216:219], v[24:27]
	v_mfma_f32_16x16x32_bf16 v[12:15], v[164:167], v[224:227], v[12:15]
	v_mfma_f32_16x16x32_bf16 v[8:11], v[172:175], v[224:227], v[8:11]
	v_mfma_f32_16x16x32_bf16 v[52:55], v[176:179], v[192:195], v[52:55]
	v_mfma_f32_16x16x32_bf16 v[48:51], v[184:187], v[192:195], v[48:51]
	v_mfma_f32_16x16x32_bf16 v[36:39], v[176:179], v[204:207], v[36:39]
	v_mfma_f32_16x16x32_bf16 v[32:35], v[184:187], v[204:207], v[32:35]
	v_mfma_f32_16x16x32_bf16 v[20:23], v[176:179], v[212:215], v[20:23]
	v_mfma_f32_16x16x32_bf16 v[16:19], v[184:187], v[212:215], v[16:19]
	v_mfma_f32_16x16x32_bf16 v[4:7], v[176:179], v[220:223], v[4:7]
	v_mfma_f32_16x16x32_bf16 v[0:3], v[184:187], v[220:223], v[0:3]
	v_mfma_f32_16x16x32_bf16 v[52:55], v[180:183], v[196:199], v[52:55]
	v_mfma_f32_16x16x32_bf16 v[48:51], v[188:191], v[196:199], v[48:51]
	v_mfma_f32_16x16x32_bf16 v[36:39], v[180:183], v[208:211], v[36:39]
	v_mfma_f32_16x16x32_bf16 v[32:35], v[188:191], v[208:211], v[32:35]
	v_mfma_f32_16x16x32_bf16 v[20:23], v[180:183], v[216:219], v[20:23]
	v_mfma_f32_16x16x32_bf16 v[16:19], v[188:191], v[216:219], v[16:19]
	v_mfma_f32_16x16x32_bf16 v[4:7], v[180:183], v[224:227], v[4:7]
	v_mfma_f32_16x16x32_bf16 v[0:3], v[188:191], v[224:227], v[0:3]
	s_setprio 0
	s_barrier
	s_add_i32 s60, 0, 0x18000
	s_add_i32 s61, 0, 0x1c000
	v_add_u32_e32 v172, s60, v159
	v_add_u32_e32 v188, s61, v159
	ds_read_b128 v[144:147], v172
	ds_read_b128 v[164:167], v172 offset:1024
	ds_read_b128 v[168:171], v172 offset:2048
	ds_read_b128 v[172:175], v172 offset:3072
	ds_read_b128 v[176:179], v188
	ds_read_b128 v[180:183], v188 offset:1024
	ds_read_b128 v[184:187], v188 offset:2048
	ds_read_b128 v[188:191], v188 offset:3072
	s_add_u32 s34, s34, 0x20000
	s_addc_u32 s35, s35, 0
	s_mov_b32 m0, s47
	v_lshl_add_u64 v[234:235], s[34:35], 0, v[128:129]
	ds_read_b128 v[192:195], v163 offset:32768
	ds_read_b128 v[196:199], v163 offset:33792
	ds_read_b128 v[204:207], v163 offset:34816
	ds_read_b128 v[208:211], v163 offset:35840
	ds_read_b128 v[212:215], v163 offset:36864
	ds_read_b128 v[216:219], v163 offset:37888
	ds_read_b128 v[220:223], v163 offset:38912
	ds_read_b128 v[224:227], v163 offset:39936
	global_load_lds_dwordx4 v[234:235], off
	v_lshl_add_u64 v[234:235], s[34:35], 0, v[132:133]
	s_mov_b32 m0, s48
	s_nop 0
	global_load_lds_dwordx4 v[234:235], off
	s_waitcnt vmcnt(8)
	s_waitcnt lgkmcnt(0)
	s_barrier
	s_setprio 1
	s_waitcnt lgkmcnt(0)
	v_mfma_f32_16x16x32_bf16 v[124:127], v[144:147], v[192:195], v[124:127]
	v_mfma_f32_16x16x32_bf16 v[120:123], v[168:171], v[192:195], v[120:123]
	v_mfma_f32_16x16x32_bf16 v[108:111], v[144:147], v[204:207], v[108:111]
	v_mfma_f32_16x16x32_bf16 v[104:107], v[168:171], v[204:207], v[104:107]
	v_mfma_f32_16x16x32_bf16 v[92:95], v[144:147], v[212:215], v[92:95]
	v_mfma_f32_16x16x32_bf16 v[88:91], v[168:171], v[212:215], v[88:91]
	v_mfma_f32_16x16x32_bf16 v[76:79], v[144:147], v[220:223], v[76:79]
	v_mfma_f32_16x16x32_bf16 v[72:75], v[168:171], v[220:223], v[72:75]
	v_mfma_f32_16x16x32_bf16 v[124:127], v[164:167], v[196:199], v[124:127]
	v_mfma_f32_16x16x32_bf16 v[120:123], v[172:175], v[196:199], v[120:123]
	v_mfma_f32_16x16x32_bf16 v[108:111], v[164:167], v[208:211], v[108:111]
	v_mfma_f32_16x16x32_bf16 v[104:107], v[172:175], v[208:211], v[104:107]
	v_mfma_f32_16x16x32_bf16 v[92:95], v[164:167], v[216:219], v[92:95]
	v_mfma_f32_16x16x32_bf16 v[88:91], v[172:175], v[216:219], v[88:91]
	v_mfma_f32_16x16x32_bf16 v[76:79], v[164:167], v[224:227], v[76:79]
	v_mfma_f32_16x16x32_bf16 v[72:75], v[172:175], v[224:227], v[72:75]
	v_mfma_f32_16x16x32_bf16 v[116:119], v[176:179], v[192:195], v[116:119]
	v_mfma_f32_16x16x32_bf16 v[112:115], v[184:187], v[192:195], v[112:115]
	v_mfma_f32_16x16x32_bf16 v[100:103], v[176:179], v[204:207], v[100:103]
	v_mfma_f32_16x16x32_bf16 v[96:99], v[184:187], v[204:207], v[96:99]
	v_mfma_f32_16x16x32_bf16 v[84:87], v[176:179], v[212:215], v[84:87]
	v_mfma_f32_16x16x32_bf16 v[80:83], v[184:187], v[212:215], v[80:83]
	v_mfma_f32_16x16x32_bf16 v[68:71], v[176:179], v[220:223], v[68:71]
	v_mfma_f32_16x16x32_bf16 v[64:67], v[184:187], v[220:223], v[64:67]
	v_mfma_f32_16x16x32_bf16 v[116:119], v[180:183], v[196:199], v[116:119]
	v_mfma_f32_16x16x32_bf16 v[112:115], v[188:191], v[196:199], v[112:115]
	v_mfma_f32_16x16x32_bf16 v[100:103], v[180:183], v[208:211], v[100:103]
	v_mfma_f32_16x16x32_bf16 v[96:99], v[188:191], v[208:211], v[96:99]
	v_mfma_f32_16x16x32_bf16 v[84:87], v[180:183], v[216:219], v[84:87]
	v_mfma_f32_16x16x32_bf16 v[80:83], v[188:191], v[216:219], v[80:83]
	v_mfma_f32_16x16x32_bf16 v[68:71], v[180:183], v[224:227], v[68:71]
	v_mfma_f32_16x16x32_bf16 v[64:67], v[188:191], v[224:227], v[64:67]
	s_setprio 0
	s_barrier
	s_add_i32 s34, s60, s45
	v_lshl_add_u64 v[200:201], v[200:201], 0, s[14:15]
	s_mov_b32 m0, s34
	ds_read_b128 v[192:195], v163 offset:49152
	ds_read_b128 v[196:199], v163 offset:50176
	ds_read_b128 v[204:207], v163 offset:51200
	ds_read_b128 v[208:211], v163 offset:52224
	ds_read_b128 v[212:215], v163 offset:53248
	ds_read_b128 v[216:219], v163 offset:54272
	ds_read_b128 v[220:223], v163 offset:55296
	ds_read_b128 v[224:227], v163 offset:56320
	global_load_lds_dwordx4 v[200:201], off
	s_add_i32 m0, s34, 0x2000
	s_add_u32 s30, s30, 0x20080
	v_lshl_add_u64 v[200:201], v[228:229], 0, s[14:15]
	s_addc_u32 s31, s31, 0
	s_add_i32 s34, s61, s45
	global_load_lds_dwordx4 v[200:201], off
	v_lshl_add_u64 v[200:201], s[30:31], 0, v[130:131]
	s_mov_b32 m0, s34
	s_nop 0
	global_load_lds_dwordx4 v[200:201], off
	v_lshl_add_u64 v[200:201], s[30:31], 0, v[134:135]
	s_add_i32 m0, s34, 0x2000
	s_nop 0
	global_load_lds_dwordx4 v[200:201], off
	v_lshl_add_u64 v[200:201], v[230:231], 0, s[14:15]
	s_mov_b32 m0, s49
	s_nop 0
	global_load_lds_dwordx4 v[200:201], off
	v_lshl_add_u64 v[200:201], v[232:233], 0, s[14:15]
	s_mov_b32 m0, s50
	s_nop 0
	global_load_lds_dwordx4 v[200:201], off
	s_waitcnt vmcnt(8)
	s_waitcnt lgkmcnt(0)
	s_barrier
	s_setprio 1
	s_waitcnt lgkmcnt(0)
	v_mfma_f32_16x16x32_bf16 v[60:63], v[144:147], v[192:195], v[60:63]
	v_mfma_f32_16x16x32_bf16 v[56:59], v[168:171], v[192:195], v[56:59]
	v_mfma_f32_16x16x32_bf16 v[44:47], v[144:147], v[204:207], v[44:47]
	v_mfma_f32_16x16x32_bf16 v[40:43], v[168:171], v[204:207], v[40:43]
	v_mfma_f32_16x16x32_bf16 v[28:31], v[144:147], v[212:215], v[28:31]
	v_mfma_f32_16x16x32_bf16 v[24:27], v[168:171], v[212:215], v[24:27]
	v_mfma_f32_16x16x32_bf16 v[12:15], v[144:147], v[220:223], v[12:15]
	v_mfma_f32_16x16x32_bf16 v[8:11], v[168:171], v[220:223], v[8:11]
	v_mfma_f32_16x16x32_bf16 v[60:63], v[164:167], v[196:199], v[60:63]
	v_mfma_f32_16x16x32_bf16 v[56:59], v[172:175], v[196:199], v[56:59]
	v_mfma_f32_16x16x32_bf16 v[44:47], v[164:167], v[208:211], v[44:47]
	v_mfma_f32_16x16x32_bf16 v[40:43], v[172:175], v[208:211], v[40:43]
	v_mfma_f32_16x16x32_bf16 v[28:31], v[164:167], v[216:219], v[28:31]
	v_mfma_f32_16x16x32_bf16 v[24:27], v[172:175], v[216:219], v[24:27]
	v_mfma_f32_16x16x32_bf16 v[12:15], v[164:167], v[224:227], v[12:15]
	v_mfma_f32_16x16x32_bf16 v[8:11], v[172:175], v[224:227], v[8:11]
	v_mfma_f32_16x16x32_bf16 v[52:55], v[176:179], v[192:195], v[52:55]
	v_mfma_f32_16x16x32_bf16 v[48:51], v[184:187], v[192:195], v[48:51]
	v_mfma_f32_16x16x32_bf16 v[36:39], v[176:179], v[204:207], v[36:39]
	v_mfma_f32_16x16x32_bf16 v[32:35], v[184:187], v[204:207], v[32:35]
	v_mfma_f32_16x16x32_bf16 v[20:23], v[176:179], v[212:215], v[20:23]
	v_mfma_f32_16x16x32_bf16 v[16:19], v[184:187], v[212:215], v[16:19]
	v_mfma_f32_16x16x32_bf16 v[4:7], v[176:179], v[220:223], v[4:7]
	v_mfma_f32_16x16x32_bf16 v[0:3], v[184:187], v[220:223], v[0:3]
	v_mfma_f32_16x16x32_bf16 v[52:55], v[180:183], v[196:199], v[52:55]
	v_mfma_f32_16x16x32_bf16 v[48:51], v[188:191], v[196:199], v[48:51]
	v_mfma_f32_16x16x32_bf16 v[36:39], v[180:183], v[208:211], v[36:39]
	v_mfma_f32_16x16x32_bf16 v[32:35], v[188:191], v[208:211], v[32:35]
	v_mfma_f32_16x16x32_bf16 v[20:23], v[180:183], v[216:219], v[20:23]
	v_mfma_f32_16x16x32_bf16 v[16:19], v[188:191], v[216:219], v[16:19]
	v_mfma_f32_16x16x32_bf16 v[4:7], v[180:183], v[224:227], v[4:7]
	v_mfma_f32_16x16x32_bf16 v[0:3], v[188:191], v[224:227], v[0:3]
	s_setprio 0
	s_barrier
	s_add_i32 s59, s59, 2
	s_add_u32 s28, s28, 0x100
	s_addc_u32 s29, s29, 0
	s_add_u32 s57, s57, 0x100
	s_addc_u32 s58, s58, 0
	s_cmp_gt_u32 s59, 5
	s_cbranch_scc0 .LBB0_2238
	s_and_b64 vcc, exec, s[16:17]
	s_cbranch_vccz .LBB0_2241
	s_barrier

.LBB0_2258:
	ds_read_b128 v[144:147], v155
	ds_read_b128 v[158:161], v155 offset:1024
	ds_read_b128 v[162:165], v155 offset:2048
	ds_read_b128 v[166:169], v155 offset:3072
	ds_read_b128 v[170:173], v156
	ds_read_b128 v[174:177], v156 offset:1024
	ds_read_b128 v[178:181], v156 offset:2048
	ds_read_b128 v[182:185], v156 offset:3072
	s_add_u32 s26, s24, 0xfffe0080
	s_addc_u32 s27, s25, -1
	s_cmp_eq_u32 s52, 4
	s_cselect_b32 s29, s17, s27
	s_cselect_b32 s28, s48, s26
	s_cselect_b32 s27, s15, s51
	s_cselect_b32 s26, s49, s50
	v_lshl_add_u64 v[148:149], s[24:25], 0, v[136:137]
	s_add_i32 m0, s23, 0xc000
	ds_read_b128 v[186:189], v157
	ds_read_b128 v[190:193], v157 offset:1024
	ds_read_b128 v[194:197], v157 offset:2048
	ds_read_b128 v[198:201], v157 offset:3072
	ds_read_b128 v[204:207], v157 offset:4096
	ds_read_b128 v[208:211], v157 offset:5120
	ds_read_b128 v[212:215], v157 offset:6144
	ds_read_b128 v[216:219], v157 offset:7168
	global_load_lds_dwordx4 v[148:149], off
	v_lshl_add_u64 v[148:149], s[24:25], 0, v[138:139]
	s_add_i32 m0, s23, 0xe000
	s_nop 0
	global_load_lds_dwordx4 v[148:149], off
	s_waitcnt vmcnt(8)
	s_waitcnt lgkmcnt(0)
	s_barrier
	s_setprio 1
	s_waitcnt lgkmcnt(0)
	v_mfma_f32_16x16x32_bf16 v[124:127], v[144:147], v[186:189], v[124:127]
	v_mfma_f32_16x16x32_bf16 v[120:123], v[162:165], v[186:189], v[120:123]
	v_mfma_f32_16x16x32_bf16 v[108:111], v[144:147], v[194:197], v[108:111]
	v_mfma_f32_16x16x32_bf16 v[104:107], v[162:165], v[194:197], v[104:107]
	v_mfma_f32_16x16x32_bf16 v[92:95], v[144:147], v[204:207], v[92:95]
	v_mfma_f32_16x16x32_bf16 v[88:91], v[162:165], v[204:207], v[88:91]
	v_mfma_f32_16x16x32_bf16 v[76:79], v[144:147], v[212:215], v[76:79]
	v_mfma_f32_16x16x32_bf16 v[72:75], v[162:165], v[212:215], v[72:75]
	v_mfma_f32_16x16x32_bf16 v[124:127], v[158:161], v[190:193], v[124:127]
	v_mfma_f32_16x16x32_bf16 v[120:123], v[166:169], v[190:193], v[120:123]
	v_mfma_f32_16x16x32_bf16 v[108:111], v[158:161], v[198:201], v[108:111]
	v_mfma_f32_16x16x32_bf16 v[104:107], v[166:169], v[198:201], v[104:107]
	v_mfma_f32_16x16x32_bf16 v[92:95], v[158:161], v[208:211], v[92:95]
	v_mfma_f32_16x16x32_bf16 v[88:91], v[166:169], v[208:211], v[88:91]
	v_mfma_f32_16x16x32_bf16 v[76:79], v[158:161], v[216:219], v[76:79]
	v_mfma_f32_16x16x32_bf16 v[72:75], v[166:169], v[216:219], v[72:75]
	v_mfma_f32_16x16x32_bf16 v[116:119], v[170:173], v[186:189], v[116:119]
	v_mfma_f32_16x16x32_bf16 v[112:115], v[178:181], v[186:189], v[112:115]
	v_mfma_f32_16x16x32_bf16 v[100:103], v[170:173], v[194:197], v[100:103]
	v_mfma_f32_16x16x32_bf16 v[96:99], v[178:181], v[194:197], v[96:99]
	v_mfma_f32_16x16x32_bf16 v[84:87], v[170:173], v[204:207], v[84:87]
	v_mfma_f32_16x16x32_bf16 v[80:83], v[178:181], v[204:207], v[80:83]
	v_mfma_f32_16x16x32_bf16 v[68:71], v[170:173], v[212:215], v[68:71]
	v_mfma_f32_16x16x32_bf16 v[64:67], v[178:181], v[212:215], v[64:67]
	v_mfma_f32_16x16x32_bf16 v[116:119], v[174:177], v[190:193], v[116:119]
	v_mfma_f32_16x16x32_bf16 v[112:115], v[182:185], v[190:193], v[112:115]
	v_mfma_f32_16x16x32_bf16 v[100:103], v[174:177], v[198:201], v[100:103]
	v_mfma_f32_16x16x32_bf16 v[96:99], v[182:185], v[198:201], v[96:99]
	v_mfma_f32_16x16x32_bf16 v[84:87], v[174:177], v[208:211], v[84:87]
	v_mfma_f32_16x16x32_bf16 v[80:83], v[182:185], v[208:211], v[80:83]
	v_mfma_f32_16x16x32_bf16 v[68:71], v[174:177], v[216:219], v[68:71]
	v_mfma_f32_16x16x32_bf16 v[64:67], v[182:185], v[216:219], v[64:67]
	s_setprio 0
	s_barrier
	s_add_i32 s53, s45, s30
	v_lshl_add_u64 v[148:149], s[26:27], 0, v[130:131]
	s_mov_b32 m0, s53
	ds_read_b128 v[186:189], v157 offset:16384
	ds_read_b128 v[190:193], v157 offset:17408
	ds_read_b128 v[194:197], v157 offset:18432
	ds_read_b128 v[198:201], v157 offset:19456
	ds_read_b128 v[204:207], v157 offset:20480
	ds_read_b128 v[208:211], v157 offset:21504
	ds_read_b128 v[212:215], v157 offset:22528
	ds_read_b128 v[216:219], v157 offset:23552
	global_load_lds_dwordx4 v[148:149], off
	s_add_i32 m0, s53, 0x2000
	s_add_u32 s54, s26, 0x20000
	v_lshl_add_u64 v[220:221], s[26:27], 0, v[134:135]
	s_addc_u32 s55, s27, 0
	s_add_i32 s53, s46, s30
	global_load_lds_dwordx4 v[220:221], off
	v_lshl_add_u64 v[222:223], s[54:55], 0, v[130:131]
	s_mov_b32 m0, s53
	v_lshl_add_u64 v[224:225], s[28:29], 0, v[132:133]
	global_load_lds_dwordx4 v[222:223], off
	v_lshl_add_u64 v[222:223], s[54:55], 0, v[134:135]
	s_add_i32 m0, s53, 0x2000
	s_nop 0
	global_load_lds_dwordx4 v[222:223], off
	v_lshl_add_u64 v[222:223], s[28:29], 0, v[128:129]
	s_mov_b32 m0, s23
	s_nop 0
	global_load_lds_dwordx4 v[222:223], off
	s_mov_b32 m0, s39
	s_nop 0
	global_load_lds_dwordx4 v[224:225], off
	s_waitcnt vmcnt(8)
	s_waitcnt lgkmcnt(0)
	s_barrier
	s_setprio 1
	s_waitcnt lgkmcnt(0)
	v_mfma_f32_16x16x32_bf16 v[60:63], v[144:147], v[186:189], v[60:63]
	v_mfma_f32_16x16x32_bf16 v[56:59], v[162:165], v[186:189], v[56:59]
	v_mfma_f32_16x16x32_bf16 v[44:47], v[144:147], v[194:197], v[44:47]
	v_mfma_f32_16x16x32_bf16 v[40:43], v[162:165], v[194:197], v[40:43]
	v_mfma_f32_16x16x32_bf16 v[28:31], v[144:147], v[204:207], v[28:31]
	v_mfma_f32_16x16x32_bf16 v[24:27], v[162:165], v[204:207], v[24:27]
	v_mfma_f32_16x16x32_bf16 v[12:15], v[144:147], v[212:215], v[12:15]
	v_mfma_f32_16x16x32_bf16 v[8:11], v[162:165], v[212:215], v[8:11]
	v_mfma_f32_16x16x32_bf16 v[60:63], v[158:161], v[190:193], v[60:63]
	v_mfma_f32_16x16x32_bf16 v[56:59], v[166:169], v[190:193], v[56:59]
	v_mfma_f32_16x16x32_bf16 v[44:47], v[158:161], v[198:201], v[44:47]
	v_mfma_f32_16x16x32_bf16 v[40:43], v[166:169], v[198:201], v[40:43]
	v_mfma_f32_16x16x32_bf16 v[28:31], v[158:161], v[208:211], v[28:31]
	v_mfma_f32_16x16x32_bf16 v[24:27], v[166:169], v[208:211], v[24:27]
	v_mfma_f32_16x16x32_bf16 v[12:15], v[158:161], v[216:219], v[12:15]
	v_mfma_f32_16x16x32_bf16 v[8:11], v[166:169], v[216:219], v[8:11]
	v_mfma_f32_16x16x32_bf16 v[52:55], v[170:173], v[186:189], v[52:55]
	v_mfma_f32_16x16x32_bf16 v[48:51], v[178:181], v[186:189], v[48:51]
	v_mfma_f32_16x16x32_bf16 v[36:39], v[170:173], v[194:197], v[36:39]
	v_mfma_f32_16x16x32_bf16 v[32:35], v[178:181], v[194:197], v[32:35]
	v_mfma_f32_16x16x32_bf16 v[20:23], v[170:173], v[204:207], v[20:23]
	v_mfma_f32_16x16x32_bf16 v[16:19], v[178:181], v[204:207], v[16:19]
	v_mfma_f32_16x16x32_bf16 v[4:7], v[170:173], v[212:215], v[4:7]
	v_mfma_f32_16x16x32_bf16 v[0:3], v[178:181], v[212:215], v[0:3]
	v_mfma_f32_16x16x32_bf16 v[52:55], v[174:177], v[190:193], v[52:55]
	v_mfma_f32_16x16x32_bf16 v[48:51], v[182:185], v[190:193], v[48:51]
	v_mfma_f32_16x16x32_bf16 v[36:39], v[174:177], v[198:201], v[36:39]
	v_mfma_f32_16x16x32_bf16 v[32:35], v[182:185], v[198:201], v[32:35]
	v_mfma_f32_16x16x32_bf16 v[20:23], v[174:177], v[208:211], v[20:23]
	v_mfma_f32_16x16x32_bf16 v[16:19], v[182:185], v[208:211], v[16:19]
	v_mfma_f32_16x16x32_bf16 v[4:7], v[174:177], v[216:219], v[4:7]
	v_mfma_f32_16x16x32_bf16 v[0:3], v[182:185], v[216:219], v[0:3]
	s_setprio 0
	s_barrier
	s_add_i32 s53, 0, 0x18000
	s_add_i32 s54, 0, 0x1c000
	v_add_u32_e32 v166, s53, v151
	v_add_u32_e32 v182, s54, v151
	ds_read_b128 v[144:147], v166
	ds_read_b128 v[158:161], v166 offset:1024
	ds_read_b128 v[162:165], v166 offset:2048
	ds_read_b128 v[166:169], v166 offset:3072
	ds_read_b128 v[170:173], v182
	ds_read_b128 v[174:177], v182 offset:1024
	ds_read_b128 v[178:181], v182 offset:2048
	ds_read_b128 v[182:185], v182 offset:3072
	s_add_u32 s28, s28, 0x20000
	s_addc_u32 s29, s29, 0
	s_mov_b32 m0, s40
	v_lshl_add_u64 v[226:227], s[28:29], 0, v[128:129]
	ds_read_b128 v[186:189], v157 offset:32768
	ds_read_b128 v[190:193], v157 offset:33792
	ds_read_b128 v[194:197], v157 offset:34816
	ds_read_b128 v[198:201], v157 offset:35840
	ds_read_b128 v[204:207], v157 offset:36864
	ds_read_b128 v[208:211], v157 offset:37888
	ds_read_b128 v[212:215], v157 offset:38912
	ds_read_b128 v[216:219], v157 offset:39936
	global_load_lds_dwordx4 v[226:227], off
	v_lshl_add_u64 v[226:227], s[28:29], 0, v[132:133]
	s_mov_b32 m0, s41
	s_nop 0
	global_load_lds_dwordx4 v[226:227], off
	s_waitcnt vmcnt(8)
	s_waitcnt lgkmcnt(0)
	s_barrier
	s_setprio 1
	s_waitcnt lgkmcnt(0)
	v_mfma_f32_16x16x32_bf16 v[124:127], v[144:147], v[186:189], v[124:127]
	v_mfma_f32_16x16x32_bf16 v[120:123], v[162:165], v[186:189], v[120:123]
	v_mfma_f32_16x16x32_bf16 v[108:111], v[144:147], v[194:197], v[108:111]
	v_mfma_f32_16x16x32_bf16 v[104:107], v[162:165], v[194:197], v[104:107]
	v_mfma_f32_16x16x32_bf16 v[92:95], v[144:147], v[204:207], v[92:95]
	v_mfma_f32_16x16x32_bf16 v[88:91], v[162:165], v[204:207], v[88:91]
	v_mfma_f32_16x16x32_bf16 v[76:79], v[144:147], v[212:215], v[76:79]
	v_mfma_f32_16x16x32_bf16 v[72:75], v[162:165], v[212:215], v[72:75]
	v_mfma_f32_16x16x32_bf16 v[124:127], v[158:161], v[190:193], v[124:127]
	v_mfma_f32_16x16x32_bf16 v[120:123], v[166:169], v[190:193], v[120:123]
	v_mfma_f32_16x16x32_bf16 v[108:111], v[158:161], v[198:201], v[108:111]
	v_mfma_f32_16x16x32_bf16 v[104:107], v[166:169], v[198:201], v[104:107]
	v_mfma_f32_16x16x32_bf16 v[92:95], v[158:161], v[208:211], v[92:95]
	v_mfma_f32_16x16x32_bf16 v[88:91], v[166:169], v[208:211], v[88:91]
	v_mfma_f32_16x16x32_bf16 v[76:79], v[158:161], v[216:219], v[76:79]
	v_mfma_f32_16x16x32_bf16 v[72:75], v[166:169], v[216:219], v[72:75]
	v_mfma_f32_16x16x32_bf16 v[116:119], v[170:173], v[186:189], v[116:119]
	v_mfma_f32_16x16x32_bf16 v[112:115], v[178:181], v[186:189], v[112:115]
	v_mfma_f32_16x16x32_bf16 v[100:103], v[170:173], v[194:197], v[100:103]
	v_mfma_f32_16x16x32_bf16 v[96:99], v[178:181], v[194:197], v[96:99]
	v_mfma_f32_16x16x32_bf16 v[84:87], v[170:173], v[204:207], v[84:87]
	v_mfma_f32_16x16x32_bf16 v[80:83], v[178:181], v[204:207], v[80:83]
	v_mfma_f32_16x16x32_bf16 v[68:71], v[170:173], v[212:215], v[68:71]
	v_mfma_f32_16x16x32_bf16 v[64:67], v[178:181], v[212:215], v[64:67]
	v_mfma_f32_16x16x32_bf16 v[116:119], v[174:177], v[190:193], v[116:119]
	v_mfma_f32_16x16x32_bf16 v[112:115], v[182:185], v[190:193], v[112:115]
	v_mfma_f32_16x16x32_bf16 v[100:103], v[174:177], v[198:201], v[100:103]
	v_mfma_f32_16x16x32_bf16 v[96:99], v[182:185], v[198:201], v[96:99]
	v_mfma_f32_16x16x32_bf16 v[84:87], v[174:177], v[208:211], v[84:87]
	v_mfma_f32_16x16x32_bf16 v[80:83], v[182:185], v[208:211], v[80:83]
	v_mfma_f32_16x16x32_bf16 v[68:71], v[174:177], v[216:219], v[68:71]
	v_mfma_f32_16x16x32_bf16 v[64:67], v[182:185], v[216:219], v[64:67]
	s_setprio 0
	s_barrier
	s_add_i32 s28, s53, s30
	v_lshl_add_u64 v[148:149], v[148:149], 0, s[10:11]
	s_mov_b32 m0, s28
	ds_read_b128 v[186:189], v157 offset:49152
	ds_read_b128 v[190:193], v157 offset:50176
	ds_read_b128 v[194:197], v157 offset:51200
	ds_read_b128 v[198:201], v157 offset:52224
	ds_read_b128 v[204:207], v157 offset:53248
	ds_read_b128 v[208:211], v157 offset:54272
	ds_read_b128 v[212:215], v157 offset:55296
	ds_read_b128 v[216:219], v157 offset:56320
	global_load_lds_dwordx4 v[148:149], off
	s_add_i32 m0, s28, 0x2000
	s_add_u32 s26, s26, 0x20080
	v_lshl_add_u64 v[148:149], v[220:221], 0, s[10:11]
	s_addc_u32 s27, s27, 0
	s_add_i32 s28, s54, s30
	global_load_lds_dwordx4 v[148:149], off
	v_lshl_add_u64 v[148:149], s[26:27], 0, v[130:131]
	s_mov_b32 m0, s28
	s_nop 0
	global_load_lds_dwordx4 v[148:149], off
	v_lshl_add_u64 v[148:149], s[26:27], 0, v[134:135]
	s_add_i32 m0, s28, 0x2000
	s_nop 0
	global_load_lds_dwordx4 v[148:149], off
	v_lshl_add_u64 v[148:149], v[222:223], 0, s[10:11]
	s_mov_b32 m0, s43
	s_nop 0
	global_load_lds_dwordx4 v[148:149], off
	v_lshl_add_u64 v[148:149], v[224:225], 0, s[10:11]
	s_mov_b32 m0, s44
	s_nop 0
	global_load_lds_dwordx4 v[148:149], off
	s_waitcnt vmcnt(8)
	s_waitcnt lgkmcnt(0)
	s_barrier
	s_setprio 1
	s_waitcnt lgkmcnt(0)
	v_mfma_f32_16x16x32_bf16 v[60:63], v[144:147], v[186:189], v[60:63]
	v_mfma_f32_16x16x32_bf16 v[56:59], v[162:165], v[186:189], v[56:59]
	v_mfma_f32_16x16x32_bf16 v[44:47], v[144:147], v[194:197], v[44:47]
	v_mfma_f32_16x16x32_bf16 v[40:43], v[162:165], v[194:197], v[40:43]
	v_mfma_f32_16x16x32_bf16 v[28:31], v[144:147], v[204:207], v[28:31]
	v_mfma_f32_16x16x32_bf16 v[24:27], v[162:165], v[204:207], v[24:27]
	v_mfma_f32_16x16x32_bf16 v[12:15], v[144:147], v[212:215], v[12:15]
	v_mfma_f32_16x16x32_bf16 v[8:11], v[162:165], v[212:215], v[8:11]
	v_mfma_f32_16x16x32_bf16 v[60:63], v[158:161], v[190:193], v[60:63]
	v_mfma_f32_16x16x32_bf16 v[56:59], v[166:169], v[190:193], v[56:59]
	v_mfma_f32_16x16x32_bf16 v[44:47], v[158:161], v[198:201], v[44:47]
	v_mfma_f32_16x16x32_bf16 v[40:43], v[166:169], v[198:201], v[40:43]
	v_mfma_f32_16x16x32_bf16 v[28:31], v[158:161], v[208:211], v[28:31]
	v_mfma_f32_16x16x32_bf16 v[24:27], v[166:169], v[208:211], v[24:27]
	v_mfma_f32_16x16x32_bf16 v[12:15], v[158:161], v[216:219], v[12:15]
	v_mfma_f32_16x16x32_bf16 v[8:11], v[166:169], v[216:219], v[8:11]
	v_mfma_f32_16x16x32_bf16 v[52:55], v[170:173], v[186:189], v[52:55]
	v_mfma_f32_16x16x32_bf16 v[48:51], v[178:181], v[186:189], v[48:51]
	v_mfma_f32_16x16x32_bf16 v[36:39], v[170:173], v[194:197], v[36:39]
	v_mfma_f32_16x16x32_bf16 v[32:35], v[178:181], v[194:197], v[32:35]
	v_mfma_f32_16x16x32_bf16 v[20:23], v[170:173], v[204:207], v[20:23]
	v_mfma_f32_16x16x32_bf16 v[16:19], v[178:181], v[204:207], v[16:19]
	v_mfma_f32_16x16x32_bf16 v[4:7], v[170:173], v[212:215], v[4:7]
	v_mfma_f32_16x16x32_bf16 v[0:3], v[178:181], v[212:215], v[0:3]
	v_mfma_f32_16x16x32_bf16 v[52:55], v[174:177], v[190:193], v[52:55]
	v_mfma_f32_16x16x32_bf16 v[48:51], v[182:185], v[190:193], v[48:51]
	v_mfma_f32_16x16x32_bf16 v[36:39], v[174:177], v[198:201], v[36:39]
	v_mfma_f32_16x16x32_bf16 v[32:35], v[182:185], v[198:201], v[32:35]
	v_mfma_f32_16x16x32_bf16 v[20:23], v[174:177], v[208:211], v[20:23]
	v_mfma_f32_16x16x32_bf16 v[16:19], v[182:185], v[208:211], v[16:19]
	v_mfma_f32_16x16x32_bf16 v[4:7], v[174:177], v[216:219], v[4:7]
	v_mfma_f32_16x16x32_bf16 v[0:3], v[182:185], v[216:219], v[0:3]
	s_setprio 0
	s_barrier
	s_add_i32 s52, s52, 2
	s_add_u32 s24, s24, 0x100
	s_addc_u32 s25, s25, 0
	s_add_u32 s50, s50, 0x100
	s_addc_u32 s51, s51, 0
	s_cmp_gt_u32 s52, 5
	s_cbranch_scc0 .LBB0_2258
	s_and_b64 vcc, exec, s[12:13]
	s_cbranch_vccz .LBB0_2261
	s_barrier

.LBB0_2335:
	ds_read_b128 v[146:149], v151
	ds_read_b128 v[156:159], v151 offset:1024
	ds_read_b128 v[160:163], v151 offset:2048
	ds_read_b128 v[164:167], v151 offset:3072
	ds_read_b128 v[168:171], v154
	ds_read_b128 v[172:175], v154 offset:1024
	ds_read_b128 v[176:179], v154 offset:2048
	ds_read_b128 v[180:183], v154 offset:3072
	s_add_u32 s30, s28, 0xfffc0080
	s_addc_u32 s31, s29, -1
	s_cmp_eq_u32 s57, 12
	s_cselect_b32 s35, s21, s31
	s_cselect_b32 s34, s27, s30
	s_cselect_b32 s31, s19, s56
	s_cselect_b32 s30, s54, s55
	v_lshl_add_u64 v[200:201], s[28:29], 0, v[138:139]
	s_add_i32 m0, s42, 0xc000
	ds_read_b128 v[184:187], v155
	ds_read_b128 v[188:191], v155 offset:1024
	ds_read_b128 v[192:195], v155 offset:2048
	ds_read_b128 v[196:199], v155 offset:3072
	ds_read_b128 v[204:207], v155 offset:4096
	ds_read_b128 v[208:211], v155 offset:5120
	ds_read_b128 v[212:215], v155 offset:6144
	ds_read_b128 v[216:219], v155 offset:7168
	global_load_lds_dwordx4 v[200:201], off
	v_lshl_add_u64 v[200:201], s[28:29], 0, v[140:141]
	s_add_i32 m0, s42, 0xe000
	s_nop 0
	global_load_lds_dwordx4 v[200:201], off
	s_waitcnt vmcnt(8)
	s_waitcnt lgkmcnt(0)
	s_barrier
	s_setprio 1
	s_waitcnt lgkmcnt(0)
	v_mfma_f32_16x16x32_bf16 v[124:127], v[146:149], v[184:187], v[124:127]
	v_mfma_f32_16x16x32_bf16 v[120:123], v[160:163], v[184:187], v[120:123]
	v_mfma_f32_16x16x32_bf16 v[108:111], v[146:149], v[192:195], v[108:111]
	v_mfma_f32_16x16x32_bf16 v[104:107], v[160:163], v[192:195], v[104:107]
	v_mfma_f32_16x16x32_bf16 v[92:95], v[146:149], v[204:207], v[92:95]
	v_mfma_f32_16x16x32_bf16 v[88:91], v[160:163], v[204:207], v[88:91]
	v_mfma_f32_16x16x32_bf16 v[76:79], v[146:149], v[212:215], v[76:79]
	v_mfma_f32_16x16x32_bf16 v[72:75], v[160:163], v[212:215], v[72:75]
	v_mfma_f32_16x16x32_bf16 v[124:127], v[156:159], v[188:191], v[124:127]
	v_mfma_f32_16x16x32_bf16 v[120:123], v[164:167], v[188:191], v[120:123]
	v_mfma_f32_16x16x32_bf16 v[108:111], v[156:159], v[196:199], v[108:111]
	v_mfma_f32_16x16x32_bf16 v[104:107], v[164:167], v[196:199], v[104:107]
	v_mfma_f32_16x16x32_bf16 v[92:95], v[156:159], v[208:211], v[92:95]
	v_mfma_f32_16x16x32_bf16 v[88:91], v[164:167], v[208:211], v[88:91]
	v_mfma_f32_16x16x32_bf16 v[76:79], v[156:159], v[216:219], v[76:79]
	v_mfma_f32_16x16x32_bf16 v[72:75], v[164:167], v[216:219], v[72:75]
	v_mfma_f32_16x16x32_bf16 v[116:119], v[168:171], v[184:187], v[116:119]
	v_mfma_f32_16x16x32_bf16 v[112:115], v[176:179], v[184:187], v[112:115]
	v_mfma_f32_16x16x32_bf16 v[100:103], v[168:171], v[192:195], v[100:103]
	v_mfma_f32_16x16x32_bf16 v[96:99], v[176:179], v[192:195], v[96:99]
	v_mfma_f32_16x16x32_bf16 v[84:87], v[168:171], v[204:207], v[84:87]
	v_mfma_f32_16x16x32_bf16 v[80:83], v[176:179], v[204:207], v[80:83]
	v_mfma_f32_16x16x32_bf16 v[68:71], v[168:171], v[212:215], v[68:71]
	v_mfma_f32_16x16x32_bf16 v[64:67], v[176:179], v[212:215], v[64:67]
	v_mfma_f32_16x16x32_bf16 v[116:119], v[172:175], v[188:191], v[116:119]
	v_mfma_f32_16x16x32_bf16 v[112:115], v[180:183], v[188:191], v[112:115]
	v_mfma_f32_16x16x32_bf16 v[100:103], v[172:175], v[196:199], v[100:103]
	v_mfma_f32_16x16x32_bf16 v[96:99], v[180:183], v[196:199], v[96:99]
	v_mfma_f32_16x16x32_bf16 v[84:87], v[172:175], v[208:211], v[84:87]
	v_mfma_f32_16x16x32_bf16 v[80:83], v[180:183], v[208:211], v[80:83]
	v_mfma_f32_16x16x32_bf16 v[68:71], v[172:175], v[216:219], v[68:71]
	v_mfma_f32_16x16x32_bf16 v[64:67], v[180:183], v[216:219], v[64:67]
	s_setprio 0
	s_barrier
	s_add_i32 s58, s51, s41
	v_lshl_add_u64 v[200:201], s[30:31], 0, v[130:131]
	s_mov_b32 m0, s58
	ds_read_b128 v[184:187], v155 offset:16384
	ds_read_b128 v[188:191], v155 offset:17408
	ds_read_b128 v[192:195], v155 offset:18432
	ds_read_b128 v[196:199], v155 offset:19456
	ds_read_b128 v[204:207], v155 offset:20480
	ds_read_b128 v[208:211], v155 offset:21504
	ds_read_b128 v[212:215], v155 offset:22528
	ds_read_b128 v[216:219], v155 offset:23552
	global_load_lds_dwordx4 v[200:201], off
	s_add_i32 m0, s58, 0x2000
	s_add_u32 s58, s30, 0x40000
	v_lshl_add_u64 v[220:221], s[30:31], 0, v[134:135]
	s_addc_u32 s59, s31, 0
	s_add_i32 s60, s52, s41
	global_load_lds_dwordx4 v[220:221], off
	v_lshl_add_u64 v[222:223], s[58:59], 0, v[130:131]
	s_mov_b32 m0, s60
	v_lshl_add_u64 v[224:225], s[34:35], 0, v[132:133]
	global_load_lds_dwordx4 v[222:223], off
	v_lshl_add_u64 v[222:223], s[58:59], 0, v[134:135]
	s_add_i32 m0, s60, 0x2000
	s_nop 0
	global_load_lds_dwordx4 v[222:223], off
	v_lshl_add_u64 v[222:223], s[34:35], 0, v[128:129]
	s_mov_b32 m0, s42
	s_nop 0
	global_load_lds_dwordx4 v[222:223], off
	s_mov_b32 m0, s43
	s_nop 0
	global_load_lds_dwordx4 v[224:225], off
	s_waitcnt vmcnt(8)
	s_waitcnt lgkmcnt(0)
	s_barrier
	s_setprio 1
	s_waitcnt lgkmcnt(0)
	v_mfma_f32_16x16x32_bf16 v[60:63], v[146:149], v[184:187], v[60:63]
	v_mfma_f32_16x16x32_bf16 v[56:59], v[160:163], v[184:187], v[56:59]
	v_mfma_f32_16x16x32_bf16 v[44:47], v[146:149], v[192:195], v[44:47]
	v_mfma_f32_16x16x32_bf16 v[40:43], v[160:163], v[192:195], v[40:43]
	v_mfma_f32_16x16x32_bf16 v[28:31], v[146:149], v[204:207], v[28:31]
	v_mfma_f32_16x16x32_bf16 v[24:27], v[160:163], v[204:207], v[24:27]
	v_mfma_f32_16x16x32_bf16 v[12:15], v[146:149], v[212:215], v[12:15]
	v_mfma_f32_16x16x32_bf16 v[8:11], v[160:163], v[212:215], v[8:11]
	v_mfma_f32_16x16x32_bf16 v[60:63], v[156:159], v[188:191], v[60:63]
	v_mfma_f32_16x16x32_bf16 v[56:59], v[164:167], v[188:191], v[56:59]
	v_mfma_f32_16x16x32_bf16 v[44:47], v[156:159], v[196:199], v[44:47]
	v_mfma_f32_16x16x32_bf16 v[40:43], v[164:167], v[196:199], v[40:43]
	v_mfma_f32_16x16x32_bf16 v[28:31], v[156:159], v[208:211], v[28:31]
	v_mfma_f32_16x16x32_bf16 v[24:27], v[164:167], v[208:211], v[24:27]
	v_mfma_f32_16x16x32_bf16 v[12:15], v[156:159], v[216:219], v[12:15]
	v_mfma_f32_16x16x32_bf16 v[8:11], v[164:167], v[216:219], v[8:11]
	v_mfma_f32_16x16x32_bf16 v[52:55], v[168:171], v[184:187], v[52:55]
	v_mfma_f32_16x16x32_bf16 v[48:51], v[176:179], v[184:187], v[48:51]
	v_mfma_f32_16x16x32_bf16 v[36:39], v[168:171], v[192:195], v[36:39]
	v_mfma_f32_16x16x32_bf16 v[32:35], v[176:179], v[192:195], v[32:35]
	v_mfma_f32_16x16x32_bf16 v[20:23], v[168:171], v[204:207], v[20:23]
	v_mfma_f32_16x16x32_bf16 v[16:19], v[176:179], v[204:207], v[16:19]
	v_mfma_f32_16x16x32_bf16 v[4:7], v[168:171], v[212:215], v[4:7]
	v_mfma_f32_16x16x32_bf16 v[0:3], v[176:179], v[212:215], v[0:3]
	v_mfma_f32_16x16x32_bf16 v[52:55], v[172:175], v[188:191], v[52:55]
	v_mfma_f32_16x16x32_bf16 v[48:51], v[180:183], v[188:191], v[48:51]
	v_mfma_f32_16x16x32_bf16 v[36:39], v[172:175], v[196:199], v[36:39]
	v_mfma_f32_16x16x32_bf16 v[32:35], v[180:183], v[196:199], v[32:35]
	v_mfma_f32_16x16x32_bf16 v[20:23], v[172:175], v[208:211], v[20:23]
	v_mfma_f32_16x16x32_bf16 v[16:19], v[180:183], v[208:211], v[16:19]
	v_mfma_f32_16x16x32_bf16 v[4:7], v[172:175], v[216:219], v[4:7]
	v_mfma_f32_16x16x32_bf16 v[0:3], v[180:183], v[216:219], v[0:3]
	s_setprio 0
	s_barrier
	s_add_i32 s58, 0, 0x18000
	s_add_i32 s59, 0, 0x1c000
	v_add_u32_e32 v164, s58, v150
	v_add_u32_e32 v180, s59, v150
	ds_read_b128 v[146:149], v164
	ds_read_b128 v[156:159], v164 offset:1024
	ds_read_b128 v[160:163], v164 offset:2048
	ds_read_b128 v[164:167], v164 offset:3072
	ds_read_b128 v[168:171], v180
	ds_read_b128 v[172:175], v180 offset:1024
	ds_read_b128 v[176:179], v180 offset:2048
	ds_read_b128 v[180:183], v180 offset:3072
	s_add_u32 s34, s34, 0x40000
	s_addc_u32 s35, s35, 0
	s_mov_b32 m0, s44
	v_lshl_add_u64 v[226:227], s[34:35], 0, v[128:129]
	ds_read_b128 v[184:187], v155 offset:32768
	ds_read_b128 v[188:191], v155 offset:33792
	ds_read_b128 v[192:195], v155 offset:34816
	ds_read_b128 v[196:199], v155 offset:35840
	ds_read_b128 v[204:207], v155 offset:36864
	ds_read_b128 v[208:211], v155 offset:37888
	ds_read_b128 v[212:215], v155 offset:38912
	ds_read_b128 v[216:219], v155 offset:39936
	global_load_lds_dwordx4 v[226:227], off
	v_lshl_add_u64 v[226:227], s[34:35], 0, v[132:133]
	s_mov_b32 m0, s45
	s_nop 0
	global_load_lds_dwordx4 v[226:227], off
	s_waitcnt vmcnt(8)
	s_waitcnt lgkmcnt(0)
	s_barrier
	s_setprio 1
	s_waitcnt lgkmcnt(0)
	v_mfma_f32_16x16x32_bf16 v[124:127], v[146:149], v[184:187], v[124:127]
	v_mfma_f32_16x16x32_bf16 v[120:123], v[160:163], v[184:187], v[120:123]
	v_mfma_f32_16x16x32_bf16 v[108:111], v[146:149], v[192:195], v[108:111]
	v_mfma_f32_16x16x32_bf16 v[104:107], v[160:163], v[192:195], v[104:107]
	v_mfma_f32_16x16x32_bf16 v[92:95], v[146:149], v[204:207], v[92:95]
	v_mfma_f32_16x16x32_bf16 v[88:91], v[160:163], v[204:207], v[88:91]
	v_mfma_f32_16x16x32_bf16 v[76:79], v[146:149], v[212:215], v[76:79]
	v_mfma_f32_16x16x32_bf16 v[72:75], v[160:163], v[212:215], v[72:75]
	v_mfma_f32_16x16x32_bf16 v[124:127], v[156:159], v[188:191], v[124:127]
	v_mfma_f32_16x16x32_bf16 v[120:123], v[164:167], v[188:191], v[120:123]
	v_mfma_f32_16x16x32_bf16 v[108:111], v[156:159], v[196:199], v[108:111]
	v_mfma_f32_16x16x32_bf16 v[104:107], v[164:167], v[196:199], v[104:107]
	v_mfma_f32_16x16x32_bf16 v[92:95], v[156:159], v[208:211], v[92:95]
	v_mfma_f32_16x16x32_bf16 v[88:91], v[164:167], v[208:211], v[88:91]
	v_mfma_f32_16x16x32_bf16 v[76:79], v[156:159], v[216:219], v[76:79]
	v_mfma_f32_16x16x32_bf16 v[72:75], v[164:167], v[216:219], v[72:75]
	v_mfma_f32_16x16x32_bf16 v[116:119], v[168:171], v[184:187], v[116:119]
	v_mfma_f32_16x16x32_bf16 v[112:115], v[176:179], v[184:187], v[112:115]
	v_mfma_f32_16x16x32_bf16 v[100:103], v[168:171], v[192:195], v[100:103]
	v_mfma_f32_16x16x32_bf16 v[96:99], v[176:179], v[192:195], v[96:99]
	v_mfma_f32_16x16x32_bf16 v[84:87], v[168:171], v[204:207], v[84:87]
	v_mfma_f32_16x16x32_bf16 v[80:83], v[176:179], v[204:207], v[80:83]
	v_mfma_f32_16x16x32_bf16 v[68:71], v[168:171], v[212:215], v[68:71]
	v_mfma_f32_16x16x32_bf16 v[64:67], v[176:179], v[212:215], v[64:67]
	v_mfma_f32_16x16x32_bf16 v[116:119], v[172:175], v[188:191], v[116:119]
	v_mfma_f32_16x16x32_bf16 v[112:115], v[180:183], v[188:191], v[112:115]
	v_mfma_f32_16x16x32_bf16 v[100:103], v[172:175], v[196:199], v[100:103]
	v_mfma_f32_16x16x32_bf16 v[96:99], v[180:183], v[196:199], v[96:99]
	v_mfma_f32_16x16x32_bf16 v[84:87], v[172:175], v[208:211], v[84:87]
	v_mfma_f32_16x16x32_bf16 v[80:83], v[180:183], v[208:211], v[80:83]
	v_mfma_f32_16x16x32_bf16 v[68:71], v[172:175], v[216:219], v[68:71]
	v_mfma_f32_16x16x32_bf16 v[64:67], v[180:183], v[216:219], v[64:67]
	s_setprio 0
	s_barrier
	s_add_i32 s34, s58, s41
	v_lshl_add_u64 v[200:201], v[200:201], 0, s[14:15]
	s_mov_b32 m0, s34
	ds_read_b128 v[184:187], v155 offset:49152
	ds_read_b128 v[188:191], v155 offset:50176
	ds_read_b128 v[192:195], v155 offset:51200
	ds_read_b128 v[196:199], v155 offset:52224
	ds_read_b128 v[204:207], v155 offset:53248
	ds_read_b128 v[208:211], v155 offset:54272
	ds_read_b128 v[212:215], v155 offset:55296
	ds_read_b128 v[216:219], v155 offset:56320
	global_load_lds_dwordx4 v[200:201], off
	s_add_i32 m0, s34, 0x2000
	s_add_u32 s30, s30, 0x40080
	v_lshl_add_u64 v[200:201], v[220:221], 0, s[14:15]
	s_addc_u32 s31, s31, 0
	s_add_i32 s34, s59, s41
	global_load_lds_dwordx4 v[200:201], off
	v_lshl_add_u64 v[200:201], s[30:31], 0, v[130:131]
	s_mov_b32 m0, s34
	s_nop 0
	global_load_lds_dwordx4 v[200:201], off
	v_lshl_add_u64 v[200:201], s[30:31], 0, v[134:135]
	s_add_i32 m0, s34, 0x2000
	s_nop 0
	global_load_lds_dwordx4 v[200:201], off
	v_lshl_add_u64 v[200:201], v[222:223], 0, s[14:15]
	s_mov_b32 m0, s48
	s_nop 0
	global_load_lds_dwordx4 v[200:201], off
	v_lshl_add_u64 v[200:201], v[224:225], 0, s[14:15]
	s_mov_b32 m0, s49
	s_nop 0
	global_load_lds_dwordx4 v[200:201], off
	s_waitcnt vmcnt(8)
	s_waitcnt lgkmcnt(0)
	s_barrier
	s_setprio 1
	s_waitcnt lgkmcnt(0)
	v_mfma_f32_16x16x32_bf16 v[60:63], v[146:149], v[184:187], v[60:63]
	v_mfma_f32_16x16x32_bf16 v[56:59], v[160:163], v[184:187], v[56:59]
	v_mfma_f32_16x16x32_bf16 v[44:47], v[146:149], v[192:195], v[44:47]
	v_mfma_f32_16x16x32_bf16 v[40:43], v[160:163], v[192:195], v[40:43]
	v_mfma_f32_16x16x32_bf16 v[28:31], v[146:149], v[204:207], v[28:31]
	v_mfma_f32_16x16x32_bf16 v[24:27], v[160:163], v[204:207], v[24:27]
	v_mfma_f32_16x16x32_bf16 v[12:15], v[146:149], v[212:215], v[12:15]
	v_mfma_f32_16x16x32_bf16 v[8:11], v[160:163], v[212:215], v[8:11]
	v_mfma_f32_16x16x32_bf16 v[60:63], v[156:159], v[188:191], v[60:63]
	v_mfma_f32_16x16x32_bf16 v[56:59], v[164:167], v[188:191], v[56:59]
	v_mfma_f32_16x16x32_bf16 v[44:47], v[156:159], v[196:199], v[44:47]
	v_mfma_f32_16x16x32_bf16 v[40:43], v[164:167], v[196:199], v[40:43]
	v_mfma_f32_16x16x32_bf16 v[28:31], v[156:159], v[208:211], v[28:31]
	v_mfma_f32_16x16x32_bf16 v[24:27], v[164:167], v[208:211], v[24:27]
	v_mfma_f32_16x16x32_bf16 v[12:15], v[156:159], v[216:219], v[12:15]
	v_mfma_f32_16x16x32_bf16 v[8:11], v[164:167], v[216:219], v[8:11]
	v_mfma_f32_16x16x32_bf16 v[52:55], v[168:171], v[184:187], v[52:55]
	v_mfma_f32_16x16x32_bf16 v[48:51], v[176:179], v[184:187], v[48:51]
	v_mfma_f32_16x16x32_bf16 v[36:39], v[168:171], v[192:195], v[36:39]
	v_mfma_f32_16x16x32_bf16 v[32:35], v[176:179], v[192:195], v[32:35]
	v_mfma_f32_16x16x32_bf16 v[20:23], v[168:171], v[204:207], v[20:23]
	v_mfma_f32_16x16x32_bf16 v[16:19], v[176:179], v[204:207], v[16:19]
	v_mfma_f32_16x16x32_bf16 v[4:7], v[168:171], v[212:215], v[4:7]
	v_mfma_f32_16x16x32_bf16 v[0:3], v[176:179], v[212:215], v[0:3]
	v_mfma_f32_16x16x32_bf16 v[52:55], v[172:175], v[188:191], v[52:55]
	v_mfma_f32_16x16x32_bf16 v[48:51], v[180:183], v[188:191], v[48:51]
	v_mfma_f32_16x16x32_bf16 v[36:39], v[172:175], v[196:199], v[36:39]
	v_mfma_f32_16x16x32_bf16 v[32:35], v[180:183], v[196:199], v[32:35]
	v_mfma_f32_16x16x32_bf16 v[20:23], v[172:175], v[208:211], v[20:23]
	v_mfma_f32_16x16x32_bf16 v[16:19], v[180:183], v[208:211], v[16:19]
	v_mfma_f32_16x16x32_bf16 v[4:7], v[172:175], v[216:219], v[4:7]
	v_mfma_f32_16x16x32_bf16 v[0:3], v[180:183], v[216:219], v[0:3]
	s_setprio 0
	s_barrier
	s_add_i32 s57, s57, 2
	s_add_u32 s28, s28, 0x100
	s_addc_u32 s29, s29, 0
	s_add_u32 s55, s55, 0x100
	s_addc_u32 s56, s56, 0
	s_cmp_gt_u32 s57, 13
	s_cbranch_scc0 .LBB0_2335
	s_and_b64 vcc, exec, s[16:17]
	s_cbranch_vccz .LBB0_2338
	s_barrier

.LBB0_2426:
	ds_read_b128 v[158:161], v154
	ds_read_b128 v[162:165], v154 offset:1024
	ds_read_b128 v[166:169], v154 offset:2048
	ds_read_b128 v[170:173], v154 offset:3072
	ds_read_b128 v[174:177], v155
	ds_read_b128 v[178:181], v155 offset:1024
	ds_read_b128 v[182:185], v155 offset:2048
	ds_read_b128 v[186:189], v155 offset:3072
	s_add_u32 s26, s24, 0xfffc0080
	s_addc_u32 s27, s25, -1
	s_cmp_eq_u32 s54, 12
	s_cselect_b32 s29, s19, s27
	s_cselect_b32 s28, s50, s26
	s_cselect_b32 s27, s17, s53
	s_cselect_b32 s26, s51, s52
	v_lshl_add_u64 v[148:149], s[24:25], 0, v[140:141]
	s_add_i32 m0, s38, 0xc000
	ds_read_b128 v[190:193], v156
	ds_read_b128 v[194:197], v156 offset:1024
	ds_read_b128 v[198:201], v156 offset:2048
	ds_read_b128 v[204:207], v156 offset:3072
	ds_read_b128 v[208:211], v156 offset:4096
	ds_read_b128 v[212:215], v156 offset:5120
	ds_read_b128 v[216:219], v156 offset:6144
	ds_read_b128 v[220:223], v156 offset:7168
	global_load_lds_dwordx4 v[148:149], off
	v_lshl_add_u64 v[148:149], s[24:25], 0, v[142:143]
	s_add_i32 m0, s38, 0xe000
	s_nop 0
	global_load_lds_dwordx4 v[148:149], off
	s_waitcnt vmcnt(8)
	s_waitcnt lgkmcnt(0)
	s_barrier
	s_setprio 1
	s_waitcnt lgkmcnt(0)
	v_mfma_f32_16x16x32_bf16 v[124:127], v[158:161], v[190:193], v[124:127]
	v_mfma_f32_16x16x32_bf16 v[120:123], v[166:169], v[190:193], v[120:123]
	v_mfma_f32_16x16x32_bf16 v[108:111], v[158:161], v[198:201], v[108:111]
	v_mfma_f32_16x16x32_bf16 v[104:107], v[166:169], v[198:201], v[104:107]
	v_mfma_f32_16x16x32_bf16 v[92:95], v[158:161], v[208:211], v[92:95]
	v_mfma_f32_16x16x32_bf16 v[88:91], v[166:169], v[208:211], v[88:91]
	v_mfma_f32_16x16x32_bf16 v[76:79], v[158:161], v[216:219], v[76:79]
	v_mfma_f32_16x16x32_bf16 v[72:75], v[166:169], v[216:219], v[72:75]
	v_mfma_f32_16x16x32_bf16 v[124:127], v[162:165], v[194:197], v[124:127]
	v_mfma_f32_16x16x32_bf16 v[120:123], v[170:173], v[194:197], v[120:123]
	v_mfma_f32_16x16x32_bf16 v[108:111], v[162:165], v[204:207], v[108:111]
	v_mfma_f32_16x16x32_bf16 v[104:107], v[170:173], v[204:207], v[104:107]
	v_mfma_f32_16x16x32_bf16 v[92:95], v[162:165], v[212:215], v[92:95]
	v_mfma_f32_16x16x32_bf16 v[88:91], v[170:173], v[212:215], v[88:91]
	v_mfma_f32_16x16x32_bf16 v[76:79], v[162:165], v[220:223], v[76:79]
	v_mfma_f32_16x16x32_bf16 v[72:75], v[170:173], v[220:223], v[72:75]
	v_mfma_f32_16x16x32_bf16 v[116:119], v[174:177], v[190:193], v[116:119]
	v_mfma_f32_16x16x32_bf16 v[112:115], v[182:185], v[190:193], v[112:115]
	v_mfma_f32_16x16x32_bf16 v[100:103], v[174:177], v[198:201], v[100:103]
	v_mfma_f32_16x16x32_bf16 v[96:99], v[182:185], v[198:201], v[96:99]
	v_mfma_f32_16x16x32_bf16 v[84:87], v[174:177], v[208:211], v[84:87]
	v_mfma_f32_16x16x32_bf16 v[80:83], v[182:185], v[208:211], v[80:83]
	v_mfma_f32_16x16x32_bf16 v[68:71], v[174:177], v[216:219], v[68:71]
	v_mfma_f32_16x16x32_bf16 v[64:67], v[182:185], v[216:219], v[64:67]
	v_mfma_f32_16x16x32_bf16 v[116:119], v[178:181], v[194:197], v[116:119]
	v_mfma_f32_16x16x32_bf16 v[112:115], v[186:189], v[194:197], v[112:115]
	v_mfma_f32_16x16x32_bf16 v[100:103], v[178:181], v[204:207], v[100:103]
	v_mfma_f32_16x16x32_bf16 v[96:99], v[186:189], v[204:207], v[96:99]
	v_mfma_f32_16x16x32_bf16 v[84:87], v[178:181], v[212:215], v[84:87]
	v_mfma_f32_16x16x32_bf16 v[80:83], v[186:189], v[212:215], v[80:83]
	v_mfma_f32_16x16x32_bf16 v[68:71], v[178:181], v[220:223], v[68:71]
	v_mfma_f32_16x16x32_bf16 v[64:67], v[186:189], v[220:223], v[64:67]
	s_setprio 0
	s_barrier
	s_add_i32 s55, s46, s37
	v_lshl_add_u64 v[148:149], s[26:27], 0, v[130:131]
	s_mov_b32 m0, s55
	ds_read_b128 v[190:193], v156 offset:16384
	ds_read_b128 v[194:197], v156 offset:17408
	ds_read_b128 v[198:201], v156 offset:18432
	ds_read_b128 v[204:207], v156 offset:19456
	ds_read_b128 v[208:211], v156 offset:20480
	ds_read_b128 v[212:215], v156 offset:21504
	ds_read_b128 v[216:219], v156 offset:22528
	ds_read_b128 v[220:223], v156 offset:23552
	global_load_lds_dwordx4 v[148:149], off
	s_add_i32 m0, s55, 0x2000
	s_add_u32 s56, s26, 0x40000
	v_lshl_add_u64 v[224:225], s[26:27], 0, v[134:135]
	s_addc_u32 s57, s27, 0
	s_add_i32 s55, s47, s37
	global_load_lds_dwordx4 v[224:225], off
	v_lshl_add_u64 v[226:227], s[56:57], 0, v[130:131]
	s_mov_b32 m0, s55
	v_lshl_add_u64 v[228:229], s[28:29], 0, v[132:133]
	global_load_lds_dwordx4 v[226:227], off
	v_lshl_add_u64 v[226:227], s[56:57], 0, v[134:135]
	s_add_i32 m0, s55, 0x2000
	s_nop 0
	global_load_lds_dwordx4 v[226:227], off
	v_lshl_add_u64 v[226:227], s[28:29], 0, v[128:129]
	s_mov_b32 m0, s38
	s_nop 0
	global_load_lds_dwordx4 v[226:227], off
	s_mov_b32 m0, s39
	s_nop 0
	global_load_lds_dwordx4 v[228:229], off
	s_waitcnt vmcnt(8)
	s_waitcnt lgkmcnt(0)
	s_barrier
	s_setprio 1
	s_waitcnt lgkmcnt(0)
	v_mfma_f32_16x16x32_bf16 v[60:63], v[158:161], v[190:193], v[60:63]
	v_mfma_f32_16x16x32_bf16 v[56:59], v[166:169], v[190:193], v[56:59]
	v_mfma_f32_16x16x32_bf16 v[44:47], v[158:161], v[198:201], v[44:47]
	v_mfma_f32_16x16x32_bf16 v[40:43], v[166:169], v[198:201], v[40:43]
	v_mfma_f32_16x16x32_bf16 v[28:31], v[158:161], v[208:211], v[28:31]
	v_mfma_f32_16x16x32_bf16 v[24:27], v[166:169], v[208:211], v[24:27]
	v_mfma_f32_16x16x32_bf16 v[12:15], v[158:161], v[216:219], v[12:15]
	v_mfma_f32_16x16x32_bf16 v[8:11], v[166:169], v[216:219], v[8:11]
	v_mfma_f32_16x16x32_bf16 v[60:63], v[162:165], v[194:197], v[60:63]
	v_mfma_f32_16x16x32_bf16 v[56:59], v[170:173], v[194:197], v[56:59]
	v_mfma_f32_16x16x32_bf16 v[44:47], v[162:165], v[204:207], v[44:47]
	v_mfma_f32_16x16x32_bf16 v[40:43], v[170:173], v[204:207], v[40:43]
	v_mfma_f32_16x16x32_bf16 v[28:31], v[162:165], v[212:215], v[28:31]
	v_mfma_f32_16x16x32_bf16 v[24:27], v[170:173], v[212:215], v[24:27]
	v_mfma_f32_16x16x32_bf16 v[12:15], v[162:165], v[220:223], v[12:15]
	v_mfma_f32_16x16x32_bf16 v[8:11], v[170:173], v[220:223], v[8:11]
	v_mfma_f32_16x16x32_bf16 v[52:55], v[174:177], v[190:193], v[52:55]
	v_mfma_f32_16x16x32_bf16 v[48:51], v[182:185], v[190:193], v[48:51]
	v_mfma_f32_16x16x32_bf16 v[36:39], v[174:177], v[198:201], v[36:39]
	v_mfma_f32_16x16x32_bf16 v[32:35], v[182:185], v[198:201], v[32:35]
	v_mfma_f32_16x16x32_bf16 v[20:23], v[174:177], v[208:211], v[20:23]
	v_mfma_f32_16x16x32_bf16 v[16:19], v[182:185], v[208:211], v[16:19]
	v_mfma_f32_16x16x32_bf16 v[4:7], v[174:177], v[216:219], v[4:7]
	v_mfma_f32_16x16x32_bf16 v[0:3], v[182:185], v[216:219], v[0:3]
	v_mfma_f32_16x16x32_bf16 v[52:55], v[178:181], v[194:197], v[52:55]
	v_mfma_f32_16x16x32_bf16 v[48:51], v[186:189], v[194:197], v[48:51]
	v_mfma_f32_16x16x32_bf16 v[36:39], v[178:181], v[204:207], v[36:39]
	v_mfma_f32_16x16x32_bf16 v[32:35], v[186:189], v[204:207], v[32:35]
	v_mfma_f32_16x16x32_bf16 v[20:23], v[178:181], v[212:215], v[20:23]
	v_mfma_f32_16x16x32_bf16 v[16:19], v[186:189], v[212:215], v[16:19]
	v_mfma_f32_16x16x32_bf16 v[4:7], v[178:181], v[220:223], v[4:7]
	v_mfma_f32_16x16x32_bf16 v[0:3], v[186:189], v[220:223], v[0:3]
	s_setprio 0
	s_barrier
	s_add_i32 s55, 0, 0x18000
	s_add_i32 s56, 0, 0x1c000
	v_add_u32_e32 v170, s55, v151
	v_add_u32_e32 v186, s56, v151
	ds_read_b128 v[158:161], v170
	ds_read_b128 v[162:165], v170 offset:1024
	ds_read_b128 v[166:169], v170 offset:2048
	ds_read_b128 v[170:173], v170 offset:3072
	ds_read_b128 v[174:177], v186
	ds_read_b128 v[178:181], v186 offset:1024
	ds_read_b128 v[182:185], v186 offset:2048
	ds_read_b128 v[186:189], v186 offset:3072
	s_add_u32 s28, s28, 0x40000
	s_addc_u32 s29, s29, 0
	s_mov_b32 m0, s40
	v_lshl_add_u64 v[230:231], s[28:29], 0, v[128:129]
	ds_read_b128 v[190:193], v156 offset:32768
	ds_read_b128 v[194:197], v156 offset:33792
	ds_read_b128 v[198:201], v156 offset:34816
	ds_read_b128 v[204:207], v156 offset:35840
	ds_read_b128 v[208:211], v156 offset:36864
	ds_read_b128 v[212:215], v156 offset:37888
	ds_read_b128 v[216:219], v156 offset:38912
	ds_read_b128 v[220:223], v156 offset:39936
	global_load_lds_dwordx4 v[230:231], off
	v_lshl_add_u64 v[230:231], s[28:29], 0, v[132:133]
	s_mov_b32 m0, s41
	s_nop 0
	global_load_lds_dwordx4 v[230:231], off
	s_waitcnt vmcnt(8)
	s_waitcnt lgkmcnt(0)
	s_barrier
	s_setprio 1
	s_waitcnt lgkmcnt(0)
	v_mfma_f32_16x16x32_bf16 v[124:127], v[158:161], v[190:193], v[124:127]
	v_mfma_f32_16x16x32_bf16 v[120:123], v[166:169], v[190:193], v[120:123]
	v_mfma_f32_16x16x32_bf16 v[108:111], v[158:161], v[198:201], v[108:111]
	v_mfma_f32_16x16x32_bf16 v[104:107], v[166:169], v[198:201], v[104:107]
	v_mfma_f32_16x16x32_bf16 v[92:95], v[158:161], v[208:211], v[92:95]
	v_mfma_f32_16x16x32_bf16 v[88:91], v[166:169], v[208:211], v[88:91]
	v_mfma_f32_16x16x32_bf16 v[76:79], v[158:161], v[216:219], v[76:79]
	v_mfma_f32_16x16x32_bf16 v[72:75], v[166:169], v[216:219], v[72:75]
	v_mfma_f32_16x16x32_bf16 v[124:127], v[162:165], v[194:197], v[124:127]
	v_mfma_f32_16x16x32_bf16 v[120:123], v[170:173], v[194:197], v[120:123]
	v_mfma_f32_16x16x32_bf16 v[108:111], v[162:165], v[204:207], v[108:111]
	v_mfma_f32_16x16x32_bf16 v[104:107], v[170:173], v[204:207], v[104:107]
	v_mfma_f32_16x16x32_bf16 v[92:95], v[162:165], v[212:215], v[92:95]
	v_mfma_f32_16x16x32_bf16 v[88:91], v[170:173], v[212:215], v[88:91]
	v_mfma_f32_16x16x32_bf16 v[76:79], v[162:165], v[220:223], v[76:79]
	v_mfma_f32_16x16x32_bf16 v[72:75], v[170:173], v[220:223], v[72:75]
	v_mfma_f32_16x16x32_bf16 v[116:119], v[174:177], v[190:193], v[116:119]
	v_mfma_f32_16x16x32_bf16 v[112:115], v[182:185], v[190:193], v[112:115]
	v_mfma_f32_16x16x32_bf16 v[100:103], v[174:177], v[198:201], v[100:103]
	v_mfma_f32_16x16x32_bf16 v[96:99], v[182:185], v[198:201], v[96:99]
	v_mfma_f32_16x16x32_bf16 v[84:87], v[174:177], v[208:211], v[84:87]
	v_mfma_f32_16x16x32_bf16 v[80:83], v[182:185], v[208:211], v[80:83]
	v_mfma_f32_16x16x32_bf16 v[68:71], v[174:177], v[216:219], v[68:71]
	v_mfma_f32_16x16x32_bf16 v[64:67], v[182:185], v[216:219], v[64:67]
	v_mfma_f32_16x16x32_bf16 v[116:119], v[178:181], v[194:197], v[116:119]
	v_mfma_f32_16x16x32_bf16 v[112:115], v[186:189], v[194:197], v[112:115]
	v_mfma_f32_16x16x32_bf16 v[100:103], v[178:181], v[204:207], v[100:103]
	v_mfma_f32_16x16x32_bf16 v[96:99], v[186:189], v[204:207], v[96:99]
	v_mfma_f32_16x16x32_bf16 v[84:87], v[178:181], v[212:215], v[84:87]
	v_mfma_f32_16x16x32_bf16 v[80:83], v[186:189], v[212:215], v[80:83]
	v_mfma_f32_16x16x32_bf16 v[68:71], v[178:181], v[220:223], v[68:71]
	v_mfma_f32_16x16x32_bf16 v[64:67], v[186:189], v[220:223], v[64:67]
	s_setprio 0
	s_barrier
	s_add_i32 s28, s55, s37
	v_lshl_add_u64 v[148:149], v[148:149], 0, s[10:11]
	s_mov_b32 m0, s28
	ds_read_b128 v[190:193], v156 offset:49152
	ds_read_b128 v[194:197], v156 offset:50176
	ds_read_b128 v[198:201], v156 offset:51200
	ds_read_b128 v[204:207], v156 offset:52224
	ds_read_b128 v[208:211], v156 offset:53248
	ds_read_b128 v[212:215], v156 offset:54272
	ds_read_b128 v[216:219], v156 offset:55296
	ds_read_b128 v[220:223], v156 offset:56320
	global_load_lds_dwordx4 v[148:149], off
	s_add_i32 m0, s28, 0x2000
	s_add_u32 s26, s26, 0x40080
	v_lshl_add_u64 v[148:149], v[224:225], 0, s[10:11]
	s_addc_u32 s27, s27, 0
	s_add_i32 s28, s56, s37
	global_load_lds_dwordx4 v[148:149], off
	v_lshl_add_u64 v[148:149], s[26:27], 0, v[130:131]
	s_mov_b32 m0, s28
	s_nop 0
	global_load_lds_dwordx4 v[148:149], off
	v_lshl_add_u64 v[148:149], s[26:27], 0, v[134:135]
	s_add_i32 m0, s28, 0x2000
	s_nop 0
	global_load_lds_dwordx4 v[148:149], off
	v_lshl_add_u64 v[148:149], v[226:227], 0, s[10:11]
	s_mov_b32 m0, s43
	s_nop 0
	global_load_lds_dwordx4 v[148:149], off
	v_lshl_add_u64 v[148:149], v[228:229], 0, s[10:11]
	s_mov_b32 m0, s44
	s_nop 0
	global_load_lds_dwordx4 v[148:149], off
	s_waitcnt vmcnt(8)
	s_waitcnt lgkmcnt(0)
	s_barrier
	s_setprio 1
	s_waitcnt lgkmcnt(0)
	v_mfma_f32_16x16x32_bf16 v[60:63], v[158:161], v[190:193], v[60:63]
	v_mfma_f32_16x16x32_bf16 v[56:59], v[166:169], v[190:193], v[56:59]
	v_mfma_f32_16x16x32_bf16 v[44:47], v[158:161], v[198:201], v[44:47]
	v_mfma_f32_16x16x32_bf16 v[40:43], v[166:169], v[198:201], v[40:43]
	v_mfma_f32_16x16x32_bf16 v[28:31], v[158:161], v[208:211], v[28:31]
	v_mfma_f32_16x16x32_bf16 v[24:27], v[166:169], v[208:211], v[24:27]
	v_mfma_f32_16x16x32_bf16 v[12:15], v[158:161], v[216:219], v[12:15]
	v_mfma_f32_16x16x32_bf16 v[8:11], v[166:169], v[216:219], v[8:11]
	v_mfma_f32_16x16x32_bf16 v[60:63], v[162:165], v[194:197], v[60:63]
	v_mfma_f32_16x16x32_bf16 v[56:59], v[170:173], v[194:197], v[56:59]
	v_mfma_f32_16x16x32_bf16 v[44:47], v[162:165], v[204:207], v[44:47]
	v_mfma_f32_16x16x32_bf16 v[40:43], v[170:173], v[204:207], v[40:43]
	v_mfma_f32_16x16x32_bf16 v[28:31], v[162:165], v[212:215], v[28:31]
	v_mfma_f32_16x16x32_bf16 v[24:27], v[170:173], v[212:215], v[24:27]
	v_mfma_f32_16x16x32_bf16 v[12:15], v[162:165], v[220:223], v[12:15]
	v_mfma_f32_16x16x32_bf16 v[8:11], v[170:173], v[220:223], v[8:11]
	v_mfma_f32_16x16x32_bf16 v[52:55], v[174:177], v[190:193], v[52:55]
	v_mfma_f32_16x16x32_bf16 v[48:51], v[182:185], v[190:193], v[48:51]
	v_mfma_f32_16x16x32_bf16 v[36:39], v[174:177], v[198:201], v[36:39]
	v_mfma_f32_16x16x32_bf16 v[32:35], v[182:185], v[198:201], v[32:35]
	v_mfma_f32_16x16x32_bf16 v[20:23], v[174:177], v[208:211], v[20:23]
	v_mfma_f32_16x16x32_bf16 v[16:19], v[182:185], v[208:211], v[16:19]
	v_mfma_f32_16x16x32_bf16 v[4:7], v[174:177], v[216:219], v[4:7]
	v_mfma_f32_16x16x32_bf16 v[0:3], v[182:185], v[216:219], v[0:3]
	v_mfma_f32_16x16x32_bf16 v[52:55], v[178:181], v[194:197], v[52:55]
	v_mfma_f32_16x16x32_bf16 v[48:51], v[186:189], v[194:197], v[48:51]
	v_mfma_f32_16x16x32_bf16 v[36:39], v[178:181], v[204:207], v[36:39]
	v_mfma_f32_16x16x32_bf16 v[32:35], v[186:189], v[204:207], v[32:35]
	v_mfma_f32_16x16x32_bf16 v[20:23], v[178:181], v[212:215], v[20:23]
	v_mfma_f32_16x16x32_bf16 v[16:19], v[186:189], v[212:215], v[16:19]
	v_mfma_f32_16x16x32_bf16 v[4:7], v[178:181], v[220:223], v[4:7]
	v_mfma_f32_16x16x32_bf16 v[0:3], v[186:189], v[220:223], v[0:3]
	s_setprio 0
	s_barrier
	s_add_i32 s54, s54, 2
	s_add_u32 s24, s24, 0x100
	s_addc_u32 s25, s25, 0
	s_add_u32 s52, s52, 0x100
	s_addc_u32 s53, s53, 0
	s_cmp_gt_u32 s54, 13
	s_cbranch_scc0 .LBB0_2426
	s_and_b64 vcc, exec, s[14:15]
	s_cbranch_vccz .LBB0_2429
	s_barrier

.LBB0_2653:
	ds_read_b128 v[148:151], v156
	ds_read_b128 v[160:163], v156 offset:1024
	ds_read_b128 v[164:167], v156 offset:2048
	ds_read_b128 v[168:171], v156 offset:3072
	ds_read_b128 v[172:175], v157
	ds_read_b128 v[176:179], v157 offset:1024
	ds_read_b128 v[180:183], v157 offset:2048
	ds_read_b128 v[184:187], v157 offset:3072
	s_add_u32 s26, s24, 0xfffc0080
	s_addc_u32 s27, s25, -1
	s_cmp_eq_u32 s56, 12
	s_cselect_b32 s29, s19, s27
	s_cselect_b32 s28, s52, s26
	s_cselect_b32 s27, s17, s55
	s_cselect_b32 s26, s53, s54
	v_lshl_add_u64 v[200:201], s[24:25], 0, v[140:141]
	s_add_i32 m0, s39, 0xc000
	ds_read_b128 v[188:191], v158
	ds_read_b128 v[192:195], v158 offset:1024
	ds_read_b128 v[196:199], v158 offset:2048
	ds_read_b128 v[204:207], v158 offset:3072
	ds_read_b128 v[208:211], v158 offset:4096
	ds_read_b128 v[212:215], v158 offset:5120
	ds_read_b128 v[216:219], v158 offset:6144
	ds_read_b128 v[220:223], v158 offset:7168
	global_load_lds_dwordx4 v[200:201], off
	v_lshl_add_u64 v[200:201], s[24:25], 0, v[142:143]
	s_add_i32 m0, s39, 0xe000
	s_nop 0
	global_load_lds_dwordx4 v[200:201], off
	s_waitcnt vmcnt(8)
	s_waitcnt lgkmcnt(0)
	s_barrier
	s_setprio 1
	s_waitcnt lgkmcnt(0)
	v_mfma_f32_16x16x32_bf16 v[124:127], v[148:151], v[188:191], v[124:127]
	v_mfma_f32_16x16x32_bf16 v[120:123], v[164:167], v[188:191], v[120:123]
	v_mfma_f32_16x16x32_bf16 v[108:111], v[148:151], v[196:199], v[108:111]
	v_mfma_f32_16x16x32_bf16 v[104:107], v[164:167], v[196:199], v[104:107]
	v_mfma_f32_16x16x32_bf16 v[92:95], v[148:151], v[208:211], v[92:95]
	v_mfma_f32_16x16x32_bf16 v[88:91], v[164:167], v[208:211], v[88:91]
	v_mfma_f32_16x16x32_bf16 v[76:79], v[148:151], v[216:219], v[76:79]
	v_mfma_f32_16x16x32_bf16 v[72:75], v[164:167], v[216:219], v[72:75]
	v_mfma_f32_16x16x32_bf16 v[124:127], v[160:163], v[192:195], v[124:127]
	v_mfma_f32_16x16x32_bf16 v[120:123], v[168:171], v[192:195], v[120:123]
	v_mfma_f32_16x16x32_bf16 v[108:111], v[160:163], v[204:207], v[108:111]
	v_mfma_f32_16x16x32_bf16 v[104:107], v[168:171], v[204:207], v[104:107]
	v_mfma_f32_16x16x32_bf16 v[92:95], v[160:163], v[212:215], v[92:95]
	v_mfma_f32_16x16x32_bf16 v[88:91], v[168:171], v[212:215], v[88:91]
	v_mfma_f32_16x16x32_bf16 v[76:79], v[160:163], v[220:223], v[76:79]
	v_mfma_f32_16x16x32_bf16 v[72:75], v[168:171], v[220:223], v[72:75]
	v_mfma_f32_16x16x32_bf16 v[116:119], v[172:175], v[188:191], v[116:119]
	v_mfma_f32_16x16x32_bf16 v[112:115], v[180:183], v[188:191], v[112:115]
	v_mfma_f32_16x16x32_bf16 v[100:103], v[172:175], v[196:199], v[100:103]
	v_mfma_f32_16x16x32_bf16 v[96:99], v[180:183], v[196:199], v[96:99]
	v_mfma_f32_16x16x32_bf16 v[84:87], v[172:175], v[208:211], v[84:87]
	v_mfma_f32_16x16x32_bf16 v[80:83], v[180:183], v[208:211], v[80:83]
	v_mfma_f32_16x16x32_bf16 v[68:71], v[172:175], v[216:219], v[68:71]
	v_mfma_f32_16x16x32_bf16 v[64:67], v[180:183], v[216:219], v[64:67]
	v_mfma_f32_16x16x32_bf16 v[116:119], v[176:179], v[192:195], v[116:119]
	v_mfma_f32_16x16x32_bf16 v[112:115], v[184:187], v[192:195], v[112:115]
	v_mfma_f32_16x16x32_bf16 v[100:103], v[176:179], v[204:207], v[100:103]
	v_mfma_f32_16x16x32_bf16 v[96:99], v[184:187], v[204:207], v[96:99]
	v_mfma_f32_16x16x32_bf16 v[84:87], v[176:179], v[212:215], v[84:87]
	v_mfma_f32_16x16x32_bf16 v[80:83], v[184:187], v[212:215], v[80:83]
	v_mfma_f32_16x16x32_bf16 v[68:71], v[176:179], v[220:223], v[68:71]
	v_mfma_f32_16x16x32_bf16 v[64:67], v[184:187], v[220:223], v[64:67]
	s_setprio 0
	s_barrier
	s_add_i32 s57, s47, s38
	v_lshl_add_u64 v[200:201], s[26:27], 0, v[132:133]
	s_mov_b32 m0, s57
	ds_read_b128 v[188:191], v158 offset:16384
	ds_read_b128 v[192:195], v158 offset:17408
	ds_read_b128 v[196:199], v158 offset:18432
	ds_read_b128 v[204:207], v158 offset:19456
	ds_read_b128 v[208:211], v158 offset:20480
	ds_read_b128 v[212:215], v158 offset:21504
	ds_read_b128 v[216:219], v158 offset:22528
	ds_read_b128 v[220:223], v158 offset:23552
	global_load_lds_dwordx4 v[200:201], off
	s_add_i32 m0, s57, 0x2000
	s_add_u32 s58, s26, 0x40000
	v_lshl_add_u64 v[224:225], s[26:27], 0, v[128:129]
	s_addc_u32 s59, s27, 0
	s_add_i32 s57, s48, s38
	global_load_lds_dwordx4 v[224:225], off
	v_lshl_add_u64 v[226:227], s[58:59], 0, v[132:133]
	s_mov_b32 m0, s57
	v_lshl_add_u64 v[228:229], s[28:29], 0, v[130:131]
	global_load_lds_dwordx4 v[226:227], off
	v_lshl_add_u64 v[226:227], s[58:59], 0, v[128:129]
	s_add_i32 m0, s57, 0x2000
	s_nop 0
	global_load_lds_dwordx4 v[226:227], off
	v_lshl_add_u64 v[226:227], s[28:29], 0, v[134:135]
	s_mov_b32 m0, s39
	s_nop 0
	global_load_lds_dwordx4 v[226:227], off
	s_mov_b32 m0, s40
	s_nop 0
	global_load_lds_dwordx4 v[228:229], off
	s_waitcnt vmcnt(8)
	s_waitcnt lgkmcnt(0)
	s_barrier
	s_setprio 1
	s_waitcnt lgkmcnt(0)
	v_mfma_f32_16x16x32_bf16 v[60:63], v[148:151], v[188:191], v[60:63]
	v_mfma_f32_16x16x32_bf16 v[56:59], v[164:167], v[188:191], v[56:59]
	v_mfma_f32_16x16x32_bf16 v[44:47], v[148:151], v[196:199], v[44:47]
	v_mfma_f32_16x16x32_bf16 v[40:43], v[164:167], v[196:199], v[40:43]
	v_mfma_f32_16x16x32_bf16 v[28:31], v[148:151], v[208:211], v[28:31]
	v_mfma_f32_16x16x32_bf16 v[24:27], v[164:167], v[208:211], v[24:27]
	v_mfma_f32_16x16x32_bf16 v[12:15], v[148:151], v[216:219], v[12:15]
	v_mfma_f32_16x16x32_bf16 v[8:11], v[164:167], v[216:219], v[8:11]
	v_mfma_f32_16x16x32_bf16 v[60:63], v[160:163], v[192:195], v[60:63]
	v_mfma_f32_16x16x32_bf16 v[56:59], v[168:171], v[192:195], v[56:59]
	v_mfma_f32_16x16x32_bf16 v[44:47], v[160:163], v[204:207], v[44:47]
	v_mfma_f32_16x16x32_bf16 v[40:43], v[168:171], v[204:207], v[40:43]
	v_mfma_f32_16x16x32_bf16 v[28:31], v[160:163], v[212:215], v[28:31]
	v_mfma_f32_16x16x32_bf16 v[24:27], v[168:171], v[212:215], v[24:27]
	v_mfma_f32_16x16x32_bf16 v[12:15], v[160:163], v[220:223], v[12:15]
	v_mfma_f32_16x16x32_bf16 v[8:11], v[168:171], v[220:223], v[8:11]
	v_mfma_f32_16x16x32_bf16 v[52:55], v[172:175], v[188:191], v[52:55]
	v_mfma_f32_16x16x32_bf16 v[48:51], v[180:183], v[188:191], v[48:51]
	v_mfma_f32_16x16x32_bf16 v[36:39], v[172:175], v[196:199], v[36:39]
	v_mfma_f32_16x16x32_bf16 v[32:35], v[180:183], v[196:199], v[32:35]
	v_mfma_f32_16x16x32_bf16 v[20:23], v[172:175], v[208:211], v[20:23]
	v_mfma_f32_16x16x32_bf16 v[16:19], v[180:183], v[208:211], v[16:19]
	v_mfma_f32_16x16x32_bf16 v[4:7], v[172:175], v[216:219], v[4:7]
	v_mfma_f32_16x16x32_bf16 v[0:3], v[180:183], v[216:219], v[0:3]
	v_mfma_f32_16x16x32_bf16 v[52:55], v[176:179], v[192:195], v[52:55]
	v_mfma_f32_16x16x32_bf16 v[48:51], v[184:187], v[192:195], v[48:51]
	v_mfma_f32_16x16x32_bf16 v[36:39], v[176:179], v[204:207], v[36:39]
	v_mfma_f32_16x16x32_bf16 v[32:35], v[184:187], v[204:207], v[32:35]
	v_mfma_f32_16x16x32_bf16 v[20:23], v[176:179], v[212:215], v[20:23]
	v_mfma_f32_16x16x32_bf16 v[16:19], v[184:187], v[212:215], v[16:19]
	v_mfma_f32_16x16x32_bf16 v[4:7], v[176:179], v[220:223], v[4:7]
	v_mfma_f32_16x16x32_bf16 v[0:3], v[184:187], v[220:223], v[0:3]
	s_setprio 0
	s_barrier
	s_add_i32 s57, 0, 0x18000
	s_add_i32 s58, 0, 0x1c000
	v_add_u32_e32 v168, s57, v155
	v_add_u32_e32 v184, s58, v155
	ds_read_b128 v[148:151], v168
	ds_read_b128 v[160:163], v168 offset:1024
	ds_read_b128 v[164:167], v168 offset:2048
	ds_read_b128 v[168:171], v168 offset:3072
	ds_read_b128 v[172:175], v184
	ds_read_b128 v[176:179], v184 offset:1024
	ds_read_b128 v[180:183], v184 offset:2048
	ds_read_b128 v[184:187], v184 offset:3072
	s_add_u32 s28, s28, 0x40000
	s_addc_u32 s29, s29, 0
	s_mov_b32 m0, s41
	v_lshl_add_u64 v[230:231], s[28:29], 0, v[134:135]
	ds_read_b128 v[188:191], v158 offset:32768
	ds_read_b128 v[192:195], v158 offset:33792
	ds_read_b128 v[196:199], v158 offset:34816
	ds_read_b128 v[204:207], v158 offset:35840
	ds_read_b128 v[208:211], v158 offset:36864
	ds_read_b128 v[212:215], v158 offset:37888
	ds_read_b128 v[216:219], v158 offset:38912
	ds_read_b128 v[220:223], v158 offset:39936
	global_load_lds_dwordx4 v[230:231], off
	v_lshl_add_u64 v[230:231], s[28:29], 0, v[130:131]
	s_mov_b32 m0, s42
	s_nop 0
	global_load_lds_dwordx4 v[230:231], off
	s_waitcnt vmcnt(8)
	s_waitcnt lgkmcnt(0)
	s_barrier
	s_setprio 1
	s_waitcnt lgkmcnt(0)
	v_mfma_f32_16x16x32_bf16 v[124:127], v[148:151], v[188:191], v[124:127]
	v_mfma_f32_16x16x32_bf16 v[120:123], v[164:167], v[188:191], v[120:123]
	v_mfma_f32_16x16x32_bf16 v[108:111], v[148:151], v[196:199], v[108:111]
	v_mfma_f32_16x16x32_bf16 v[104:107], v[164:167], v[196:199], v[104:107]
	v_mfma_f32_16x16x32_bf16 v[92:95], v[148:151], v[208:211], v[92:95]
	v_mfma_f32_16x16x32_bf16 v[88:91], v[164:167], v[208:211], v[88:91]
	v_mfma_f32_16x16x32_bf16 v[76:79], v[148:151], v[216:219], v[76:79]
	v_mfma_f32_16x16x32_bf16 v[72:75], v[164:167], v[216:219], v[72:75]
	v_mfma_f32_16x16x32_bf16 v[124:127], v[160:163], v[192:195], v[124:127]
	v_mfma_f32_16x16x32_bf16 v[120:123], v[168:171], v[192:195], v[120:123]
	v_mfma_f32_16x16x32_bf16 v[108:111], v[160:163], v[204:207], v[108:111]
	v_mfma_f32_16x16x32_bf16 v[104:107], v[168:171], v[204:207], v[104:107]
	v_mfma_f32_16x16x32_bf16 v[92:95], v[160:163], v[212:215], v[92:95]
	v_mfma_f32_16x16x32_bf16 v[88:91], v[168:171], v[212:215], v[88:91]
	v_mfma_f32_16x16x32_bf16 v[76:79], v[160:163], v[220:223], v[76:79]
	v_mfma_f32_16x16x32_bf16 v[72:75], v[168:171], v[220:223], v[72:75]
	v_mfma_f32_16x16x32_bf16 v[116:119], v[172:175], v[188:191], v[116:119]
	v_mfma_f32_16x16x32_bf16 v[112:115], v[180:183], v[188:191], v[112:115]
	v_mfma_f32_16x16x32_bf16 v[100:103], v[172:175], v[196:199], v[100:103]
	v_mfma_f32_16x16x32_bf16 v[96:99], v[180:183], v[196:199], v[96:99]
	v_mfma_f32_16x16x32_bf16 v[84:87], v[172:175], v[208:211], v[84:87]
	v_mfma_f32_16x16x32_bf16 v[80:83], v[180:183], v[208:211], v[80:83]
	v_mfma_f32_16x16x32_bf16 v[68:71], v[172:175], v[216:219], v[68:71]
	v_mfma_f32_16x16x32_bf16 v[64:67], v[180:183], v[216:219], v[64:67]
	v_mfma_f32_16x16x32_bf16 v[116:119], v[176:179], v[192:195], v[116:119]
	v_mfma_f32_16x16x32_bf16 v[112:115], v[184:187], v[192:195], v[112:115]
	v_mfma_f32_16x16x32_bf16 v[100:103], v[176:179], v[204:207], v[100:103]
	v_mfma_f32_16x16x32_bf16 v[96:99], v[184:187], v[204:207], v[96:99]
	v_mfma_f32_16x16x32_bf16 v[84:87], v[176:179], v[212:215], v[84:87]
	v_mfma_f32_16x16x32_bf16 v[80:83], v[184:187], v[212:215], v[80:83]
	v_mfma_f32_16x16x32_bf16 v[68:71], v[176:179], v[220:223], v[68:71]
	v_mfma_f32_16x16x32_bf16 v[64:67], v[184:187], v[220:223], v[64:67]
	s_setprio 0
	s_barrier
	s_add_i32 s28, s57, s38
	v_lshl_add_u64 v[200:201], v[200:201], 0, s[10:11]
	s_mov_b32 m0, s28
	ds_read_b128 v[188:191], v158 offset:49152
	ds_read_b128 v[192:195], v158 offset:50176
	ds_read_b128 v[196:199], v158 offset:51200
	ds_read_b128 v[204:207], v158 offset:52224
	ds_read_b128 v[208:211], v158 offset:53248
	ds_read_b128 v[212:215], v158 offset:54272
	ds_read_b128 v[216:219], v158 offset:55296
	ds_read_b128 v[220:223], v158 offset:56320
	global_load_lds_dwordx4 v[200:201], off
	s_add_i32 m0, s28, 0x2000
	s_add_u32 s26, s26, 0x40080
	v_lshl_add_u64 v[200:201], v[224:225], 0, s[10:11]
	s_addc_u32 s27, s27, 0
	s_add_i32 s28, s58, s38
	global_load_lds_dwordx4 v[200:201], off
	v_lshl_add_u64 v[200:201], s[26:27], 0, v[132:133]
	s_mov_b32 m0, s28
	s_nop 0
	global_load_lds_dwordx4 v[200:201], off
	v_lshl_add_u64 v[200:201], s[26:27], 0, v[128:129]
	s_add_i32 m0, s28, 0x2000
	s_nop 0
	global_load_lds_dwordx4 v[200:201], off
	v_lshl_add_u64 v[200:201], v[226:227], 0, s[10:11]
	s_mov_b32 m0, s43
	s_nop 0
	global_load_lds_dwordx4 v[200:201], off
	v_lshl_add_u64 v[200:201], v[228:229], 0, s[10:11]
	s_mov_b32 m0, s44
	s_nop 0
	global_load_lds_dwordx4 v[200:201], off
	s_waitcnt vmcnt(8)
	s_waitcnt lgkmcnt(0)
	s_barrier
	s_setprio 1
	s_waitcnt lgkmcnt(0)
	v_mfma_f32_16x16x32_bf16 v[60:63], v[148:151], v[188:191], v[60:63]
	v_mfma_f32_16x16x32_bf16 v[56:59], v[164:167], v[188:191], v[56:59]
	v_mfma_f32_16x16x32_bf16 v[44:47], v[148:151], v[196:199], v[44:47]
	v_mfma_f32_16x16x32_bf16 v[40:43], v[164:167], v[196:199], v[40:43]
	v_mfma_f32_16x16x32_bf16 v[28:31], v[148:151], v[208:211], v[28:31]
	v_mfma_f32_16x16x32_bf16 v[24:27], v[164:167], v[208:211], v[24:27]
	v_mfma_f32_16x16x32_bf16 v[12:15], v[148:151], v[216:219], v[12:15]
	v_mfma_f32_16x16x32_bf16 v[8:11], v[164:167], v[216:219], v[8:11]
	v_mfma_f32_16x16x32_bf16 v[60:63], v[160:163], v[192:195], v[60:63]
	v_mfma_f32_16x16x32_bf16 v[56:59], v[168:171], v[192:195], v[56:59]
	v_mfma_f32_16x16x32_bf16 v[44:47], v[160:163], v[204:207], v[44:47]
	v_mfma_f32_16x16x32_bf16 v[40:43], v[168:171], v[204:207], v[40:43]
	v_mfma_f32_16x16x32_bf16 v[28:31], v[160:163], v[212:215], v[28:31]
	v_mfma_f32_16x16x32_bf16 v[24:27], v[168:171], v[212:215], v[24:27]
	v_mfma_f32_16x16x32_bf16 v[12:15], v[160:163], v[220:223], v[12:15]
	v_mfma_f32_16x16x32_bf16 v[8:11], v[168:171], v[220:223], v[8:11]
	v_mfma_f32_16x16x32_bf16 v[52:55], v[172:175], v[188:191], v[52:55]
	v_mfma_f32_16x16x32_bf16 v[48:51], v[180:183], v[188:191], v[48:51]
	v_mfma_f32_16x16x32_bf16 v[36:39], v[172:175], v[196:199], v[36:39]
	v_mfma_f32_16x16x32_bf16 v[32:35], v[180:183], v[196:199], v[32:35]
	v_mfma_f32_16x16x32_bf16 v[20:23], v[172:175], v[208:211], v[20:23]
	v_mfma_f32_16x16x32_bf16 v[16:19], v[180:183], v[208:211], v[16:19]
	v_mfma_f32_16x16x32_bf16 v[4:7], v[172:175], v[216:219], v[4:7]
	v_mfma_f32_16x16x32_bf16 v[0:3], v[180:183], v[216:219], v[0:3]
	v_mfma_f32_16x16x32_bf16 v[52:55], v[176:179], v[192:195], v[52:55]
	v_mfma_f32_16x16x32_bf16 v[48:51], v[184:187], v[192:195], v[48:51]
	v_mfma_f32_16x16x32_bf16 v[36:39], v[176:179], v[204:207], v[36:39]
	v_mfma_f32_16x16x32_bf16 v[32:35], v[184:187], v[204:207], v[32:35]
	v_mfma_f32_16x16x32_bf16 v[20:23], v[176:179], v[212:215], v[20:23]
	v_mfma_f32_16x16x32_bf16 v[16:19], v[184:187], v[212:215], v[16:19]
	v_mfma_f32_16x16x32_bf16 v[4:7], v[176:179], v[220:223], v[4:7]
	v_mfma_f32_16x16x32_bf16 v[0:3], v[184:187], v[220:223], v[0:3]
	s_setprio 0
	s_barrier
	s_add_i32 s56, s56, 2
	s_add_u32 s24, s24, 0x100
	s_addc_u32 s25, s25, 0
	s_add_u32 s54, s54, 0x100
	s_addc_u32 s55, s55, 0
	s_cmp_gt_u32 s56, 13
	s_cbranch_scc0 .LBB0_2653
	s_and_b64 vcc, exec, s[14:15]
	s_cbranch_vccz .LBB0_2656
	s_barrier

.LBB0_2734:
	ds_read_b128 v[146:149], v151
	ds_read_b128 v[156:159], v151 offset:1024
	ds_read_b128 v[160:163], v151 offset:2048
	ds_read_b128 v[164:167], v151 offset:3072
	ds_read_b128 v[168:171], v153
	ds_read_b128 v[172:175], v153 offset:1024
	ds_read_b128 v[176:179], v153 offset:2048
	ds_read_b128 v[180:183], v153 offset:3072
	s_add_u32 s26, s24, 0xfff50080
	s_addc_u32 s27, s25, -1
	s_cmp_eq_u32 s55, 40
	s_cselect_b32 s29, s1, s27
	s_cselect_b32 s28, s0, s26
	s_cselect_b32 s27, s23, s54
	s_cselect_b32 s26, s22, s53
	v_lshl_add_u64 v[216:217], s[24:25], 0, v[138:139]
	s_add_i32 m0, s38, 0xc000
	ds_read_b128 v[184:187], v154
	ds_read_b128 v[188:191], v154 offset:1024
	ds_read_b128 v[192:195], v154 offset:2048
	ds_read_b128 v[196:199], v154 offset:3072
	ds_read_b128 v[200:203], v154 offset:4096
	ds_read_b128 v[204:207], v154 offset:5120
	ds_read_b128 v[208:211], v154 offset:6144
	ds_read_b128 v[212:215], v154 offset:7168
	global_load_lds_dwordx4 v[216:217], off
	v_lshl_add_u64 v[216:217], s[24:25], 0, v[140:141]
	s_add_i32 m0, s38, 0xe000
	s_nop 0
	global_load_lds_dwordx4 v[216:217], off
	s_waitcnt vmcnt(8)
	s_waitcnt lgkmcnt(0)
	s_barrier
	s_setprio 1
	s_waitcnt lgkmcnt(0)
	v_mfma_f32_16x16x32_bf16 v[124:127], v[146:149], v[184:187], v[124:127]
	v_mfma_f32_16x16x32_bf16 v[120:123], v[160:163], v[184:187], v[120:123]
	v_mfma_f32_16x16x32_bf16 v[108:111], v[146:149], v[192:195], v[108:111]
	v_mfma_f32_16x16x32_bf16 v[104:107], v[160:163], v[192:195], v[104:107]
	v_mfma_f32_16x16x32_bf16 v[92:95], v[146:149], v[200:203], v[92:95]
	v_mfma_f32_16x16x32_bf16 v[88:91], v[160:163], v[200:203], v[88:91]
	v_mfma_f32_16x16x32_bf16 v[76:79], v[146:149], v[208:211], v[76:79]
	v_mfma_f32_16x16x32_bf16 v[72:75], v[160:163], v[208:211], v[72:75]
	v_mfma_f32_16x16x32_bf16 v[124:127], v[156:159], v[188:191], v[124:127]
	v_mfma_f32_16x16x32_bf16 v[120:123], v[164:167], v[188:191], v[120:123]
	v_mfma_f32_16x16x32_bf16 v[108:111], v[156:159], v[196:199], v[108:111]
	v_mfma_f32_16x16x32_bf16 v[104:107], v[164:167], v[196:199], v[104:107]
	v_mfma_f32_16x16x32_bf16 v[92:95], v[156:159], v[204:207], v[92:95]
	v_mfma_f32_16x16x32_bf16 v[88:91], v[164:167], v[204:207], v[88:91]
	v_mfma_f32_16x16x32_bf16 v[76:79], v[156:159], v[212:215], v[76:79]
	v_mfma_f32_16x16x32_bf16 v[72:75], v[164:167], v[212:215], v[72:75]
	v_mfma_f32_16x16x32_bf16 v[116:119], v[168:171], v[184:187], v[116:119]
	v_mfma_f32_16x16x32_bf16 v[112:115], v[176:179], v[184:187], v[112:115]
	v_mfma_f32_16x16x32_bf16 v[100:103], v[168:171], v[192:195], v[100:103]
	v_mfma_f32_16x16x32_bf16 v[96:99], v[176:179], v[192:195], v[96:99]
	v_mfma_f32_16x16x32_bf16 v[84:87], v[168:171], v[200:203], v[84:87]
	v_mfma_f32_16x16x32_bf16 v[80:83], v[176:179], v[200:203], v[80:83]
	v_mfma_f32_16x16x32_bf16 v[68:71], v[168:171], v[208:211], v[68:71]
	v_mfma_f32_16x16x32_bf16 v[64:67], v[176:179], v[208:211], v[64:67]
	v_mfma_f32_16x16x32_bf16 v[116:119], v[172:175], v[188:191], v[116:119]
	v_mfma_f32_16x16x32_bf16 v[112:115], v[180:183], v[188:191], v[112:115]
	v_mfma_f32_16x16x32_bf16 v[100:103], v[172:175], v[196:199], v[100:103]
	v_mfma_f32_16x16x32_bf16 v[96:99], v[180:183], v[196:199], v[96:99]
	v_mfma_f32_16x16x32_bf16 v[84:87], v[172:175], v[204:207], v[84:87]
	v_mfma_f32_16x16x32_bf16 v[80:83], v[180:183], v[204:207], v[80:83]
	v_mfma_f32_16x16x32_bf16 v[68:71], v[172:175], v[212:215], v[68:71]
	v_mfma_f32_16x16x32_bf16 v[64:67], v[180:183], v[212:215], v[64:67]
	s_setprio 0
	s_barrier
	s_add_i32 s56, s47, s37
	v_lshl_add_u64 v[216:217], s[26:27], 0, v[130:131]
	s_mov_b32 m0, s56
	ds_read_b128 v[184:187], v154 offset:16384
	ds_read_b128 v[188:191], v154 offset:17408
	ds_read_b128 v[192:195], v154 offset:18432
	ds_read_b128 v[196:199], v154 offset:19456
	ds_read_b128 v[200:203], v154 offset:20480
	ds_read_b128 v[204:207], v154 offset:21504
	ds_read_b128 v[208:211], v154 offset:22528
	ds_read_b128 v[212:215], v154 offset:23552
	global_load_lds_dwordx4 v[216:217], off
	s_add_i32 m0, s56, 0x2000
	s_add_u32 s56, s26, 0xb0000
	v_lshl_add_u64 v[218:219], s[26:27], 0, v[134:135]
	s_addc_u32 s57, s27, 0
	s_add_i32 s58, s48, s37
	global_load_lds_dwordx4 v[218:219], off
	v_lshl_add_u64 v[220:221], s[56:57], 0, v[130:131]
	s_mov_b32 m0, s58
	v_lshl_add_u64 v[222:223], s[28:29], 0, v[132:133]
	global_load_lds_dwordx4 v[220:221], off
	v_lshl_add_u64 v[220:221], s[56:57], 0, v[134:135]
	s_add_i32 m0, s58, 0x2000
	s_nop 0
	global_load_lds_dwordx4 v[220:221], off
	v_lshl_add_u64 v[220:221], s[28:29], 0, v[128:129]
	s_mov_b32 m0, s38
	s_nop 0
	global_load_lds_dwordx4 v[220:221], off
	s_mov_b32 m0, s39
	s_nop 0
	global_load_lds_dwordx4 v[222:223], off
	s_waitcnt vmcnt(8)
	s_waitcnt lgkmcnt(0)
	s_barrier
	s_setprio 1
	s_waitcnt lgkmcnt(0)
	v_mfma_f32_16x16x32_bf16 v[60:63], v[146:149], v[184:187], v[60:63]
	v_mfma_f32_16x16x32_bf16 v[56:59], v[160:163], v[184:187], v[56:59]
	v_mfma_f32_16x16x32_bf16 v[44:47], v[146:149], v[192:195], v[44:47]
	v_mfma_f32_16x16x32_bf16 v[40:43], v[160:163], v[192:195], v[40:43]
	v_mfma_f32_16x16x32_bf16 v[28:31], v[146:149], v[200:203], v[28:31]
	v_mfma_f32_16x16x32_bf16 v[24:27], v[160:163], v[200:203], v[24:27]
	v_mfma_f32_16x16x32_bf16 v[12:15], v[146:149], v[208:211], v[12:15]
	v_mfma_f32_16x16x32_bf16 v[8:11], v[160:163], v[208:211], v[8:11]
	v_mfma_f32_16x16x32_bf16 v[60:63], v[156:159], v[188:191], v[60:63]
	v_mfma_f32_16x16x32_bf16 v[56:59], v[164:167], v[188:191], v[56:59]
	v_mfma_f32_16x16x32_bf16 v[44:47], v[156:159], v[196:199], v[44:47]
	v_mfma_f32_16x16x32_bf16 v[40:43], v[164:167], v[196:199], v[40:43]
	v_mfma_f32_16x16x32_bf16 v[28:31], v[156:159], v[204:207], v[28:31]
	v_mfma_f32_16x16x32_bf16 v[24:27], v[164:167], v[204:207], v[24:27]
	v_mfma_f32_16x16x32_bf16 v[12:15], v[156:159], v[212:215], v[12:15]
	v_mfma_f32_16x16x32_bf16 v[8:11], v[164:167], v[212:215], v[8:11]
	v_mfma_f32_16x16x32_bf16 v[52:55], v[168:171], v[184:187], v[52:55]
	v_mfma_f32_16x16x32_bf16 v[48:51], v[176:179], v[184:187], v[48:51]
	v_mfma_f32_16x16x32_bf16 v[36:39], v[168:171], v[192:195], v[36:39]
	v_mfma_f32_16x16x32_bf16 v[32:35], v[176:179], v[192:195], v[32:35]
	v_mfma_f32_16x16x32_bf16 v[20:23], v[168:171], v[200:203], v[20:23]
	v_mfma_f32_16x16x32_bf16 v[16:19], v[176:179], v[200:203], v[16:19]
	v_mfma_f32_16x16x32_bf16 v[4:7], v[168:171], v[208:211], v[4:7]
	v_mfma_f32_16x16x32_bf16 v[0:3], v[176:179], v[208:211], v[0:3]
	v_mfma_f32_16x16x32_bf16 v[52:55], v[172:175], v[188:191], v[52:55]
	v_mfma_f32_16x16x32_bf16 v[48:51], v[180:183], v[188:191], v[48:51]
	v_mfma_f32_16x16x32_bf16 v[36:39], v[172:175], v[196:199], v[36:39]
	v_mfma_f32_16x16x32_bf16 v[32:35], v[180:183], v[196:199], v[32:35]
	v_mfma_f32_16x16x32_bf16 v[20:23], v[172:175], v[204:207], v[20:23]
	v_mfma_f32_16x16x32_bf16 v[16:19], v[180:183], v[204:207], v[16:19]
	v_mfma_f32_16x16x32_bf16 v[4:7], v[172:175], v[212:215], v[4:7]
	v_mfma_f32_16x16x32_bf16 v[0:3], v[180:183], v[212:215], v[0:3]
	s_setprio 0
	s_barrier
	s_add_i32 s56, 0, 0x18000
	v_add_u32_e32 v155, s56, v150
	s_add_i32 s57, 0, 0x1c000
	ds_read_b128 v[146:149], v155
	ds_read_b128 v[156:159], v155 offset:1024
	ds_read_b128 v[160:163], v155 offset:2048
	ds_read_b128 v[164:167], v155 offset:3072
	v_add_u32_e32 v155, s57, v150
	ds_read_b128 v[168:171], v155
	ds_read_b128 v[172:175], v155 offset:1024
	ds_read_b128 v[176:179], v155 offset:2048
	ds_read_b128 v[180:183], v155 offset:3072
	s_add_u32 s28, s28, 0xb0000
	s_addc_u32 s29, s29, 0
	s_mov_b32 m0, s40
	v_lshl_add_u64 v[224:225], s[28:29], 0, v[128:129]
	ds_read_b128 v[184:187], v154 offset:32768
	ds_read_b128 v[188:191], v154 offset:33792
	ds_read_b128 v[192:195], v154 offset:34816
	ds_read_b128 v[196:199], v154 offset:35840
	ds_read_b128 v[200:203], v154 offset:36864
	ds_read_b128 v[204:207], v154 offset:37888
	ds_read_b128 v[208:211], v154 offset:38912
	ds_read_b128 v[212:215], v154 offset:39936
	global_load_lds_dwordx4 v[224:225], off
	v_lshl_add_u64 v[224:225], s[28:29], 0, v[132:133]
	s_mov_b32 m0, s41
	s_nop 0
	global_load_lds_dwordx4 v[224:225], off
	s_waitcnt vmcnt(8)
	s_waitcnt lgkmcnt(0)
	s_barrier
	s_setprio 1
	s_waitcnt lgkmcnt(0)
	v_mfma_f32_16x16x32_bf16 v[124:127], v[146:149], v[184:187], v[124:127]
	v_mfma_f32_16x16x32_bf16 v[120:123], v[160:163], v[184:187], v[120:123]
	v_mfma_f32_16x16x32_bf16 v[108:111], v[146:149], v[192:195], v[108:111]
	v_mfma_f32_16x16x32_bf16 v[104:107], v[160:163], v[192:195], v[104:107]
	v_mfma_f32_16x16x32_bf16 v[92:95], v[146:149], v[200:203], v[92:95]
	v_mfma_f32_16x16x32_bf16 v[88:91], v[160:163], v[200:203], v[88:91]
	v_mfma_f32_16x16x32_bf16 v[76:79], v[146:149], v[208:211], v[76:79]
	v_mfma_f32_16x16x32_bf16 v[72:75], v[160:163], v[208:211], v[72:75]
	v_mfma_f32_16x16x32_bf16 v[124:127], v[156:159], v[188:191], v[124:127]
	v_mfma_f32_16x16x32_bf16 v[120:123], v[164:167], v[188:191], v[120:123]
	v_mfma_f32_16x16x32_bf16 v[108:111], v[156:159], v[196:199], v[108:111]
	v_mfma_f32_16x16x32_bf16 v[104:107], v[164:167], v[196:199], v[104:107]
	v_mfma_f32_16x16x32_bf16 v[92:95], v[156:159], v[204:207], v[92:95]
	v_mfma_f32_16x16x32_bf16 v[88:91], v[164:167], v[204:207], v[88:91]
	v_mfma_f32_16x16x32_bf16 v[76:79], v[156:159], v[212:215], v[76:79]
	v_mfma_f32_16x16x32_bf16 v[72:75], v[164:167], v[212:215], v[72:75]
	v_mfma_f32_16x16x32_bf16 v[116:119], v[168:171], v[184:187], v[116:119]
	v_mfma_f32_16x16x32_bf16 v[112:115], v[176:179], v[184:187], v[112:115]
	v_mfma_f32_16x16x32_bf16 v[100:103], v[168:171], v[192:195], v[100:103]
	v_mfma_f32_16x16x32_bf16 v[96:99], v[176:179], v[192:195], v[96:99]
	v_mfma_f32_16x16x32_bf16 v[84:87], v[168:171], v[200:203], v[84:87]
	v_mfma_f32_16x16x32_bf16 v[80:83], v[176:179], v[200:203], v[80:83]
	v_mfma_f32_16x16x32_bf16 v[68:71], v[168:171], v[208:211], v[68:71]
	v_mfma_f32_16x16x32_bf16 v[64:67], v[176:179], v[208:211], v[64:67]
	v_mfma_f32_16x16x32_bf16 v[116:119], v[172:175], v[188:191], v[116:119]
	v_mfma_f32_16x16x32_bf16 v[112:115], v[180:183], v[188:191], v[112:115]
	v_mfma_f32_16x16x32_bf16 v[100:103], v[172:175], v[196:199], v[100:103]
	v_mfma_f32_16x16x32_bf16 v[96:99], v[180:183], v[196:199], v[96:99]
	v_mfma_f32_16x16x32_bf16 v[84:87], v[172:175], v[204:207], v[84:87]
	v_mfma_f32_16x16x32_bf16 v[80:83], v[180:183], v[204:207], v[80:83]
	v_mfma_f32_16x16x32_bf16 v[68:71], v[172:175], v[212:215], v[68:71]
	v_mfma_f32_16x16x32_bf16 v[64:67], v[180:183], v[212:215], v[64:67]
	s_setprio 0
	s_barrier
	s_add_i32 s28, s56, s37
	v_lshl_add_u64 v[216:217], v[216:217], 0, s[18:19]
	s_mov_b32 m0, s28
	ds_read_b128 v[184:187], v154 offset:49152
	ds_read_b128 v[188:191], v154 offset:50176
	ds_read_b128 v[192:195], v154 offset:51200
	ds_read_b128 v[196:199], v154 offset:52224
	ds_read_b128 v[200:203], v154 offset:53248
	ds_read_b128 v[204:207], v154 offset:54272
	ds_read_b128 v[208:211], v154 offset:55296
	ds_read_b128 v[212:215], v154 offset:56320
	global_load_lds_dwordx4 v[216:217], off
	s_add_i32 m0, s28, 0x2000
	s_add_u32 s26, s26, 0xb0080
	v_lshl_add_u64 v[216:217], v[218:219], 0, s[18:19]
	s_addc_u32 s27, s27, 0
	s_add_i32 s28, s57, s37
	global_load_lds_dwordx4 v[216:217], off
	v_lshl_add_u64 v[216:217], s[26:27], 0, v[130:131]
	s_mov_b32 m0, s28
	s_nop 0
	global_load_lds_dwordx4 v[216:217], off
	v_lshl_add_u64 v[216:217], s[26:27], 0, v[134:135]
	s_add_i32 m0, s28, 0x2000
	s_nop 0
	global_load_lds_dwordx4 v[216:217], off
	v_lshl_add_u64 v[216:217], v[220:221], 0, s[18:19]
	s_mov_b32 m0, s44
	s_nop 0
	global_load_lds_dwordx4 v[216:217], off
	v_lshl_add_u64 v[216:217], v[222:223], 0, s[18:19]
	s_mov_b32 m0, s45
	s_nop 0
	global_load_lds_dwordx4 v[216:217], off
	s_waitcnt vmcnt(8)
	s_waitcnt lgkmcnt(0)
	s_barrier
	s_setprio 1
	s_waitcnt lgkmcnt(0)
	v_mfma_f32_16x16x32_bf16 v[60:63], v[146:149], v[184:187], v[60:63]
	v_mfma_f32_16x16x32_bf16 v[56:59], v[160:163], v[184:187], v[56:59]
	v_mfma_f32_16x16x32_bf16 v[44:47], v[146:149], v[192:195], v[44:47]
	v_mfma_f32_16x16x32_bf16 v[40:43], v[160:163], v[192:195], v[40:43]
	v_mfma_f32_16x16x32_bf16 v[28:31], v[146:149], v[200:203], v[28:31]
	v_mfma_f32_16x16x32_bf16 v[24:27], v[160:163], v[200:203], v[24:27]
	v_mfma_f32_16x16x32_bf16 v[12:15], v[146:149], v[208:211], v[12:15]
	v_mfma_f32_16x16x32_bf16 v[8:11], v[160:163], v[208:211], v[8:11]
	v_mfma_f32_16x16x32_bf16 v[60:63], v[156:159], v[188:191], v[60:63]
	v_mfma_f32_16x16x32_bf16 v[56:59], v[164:167], v[188:191], v[56:59]
	v_mfma_f32_16x16x32_bf16 v[44:47], v[156:159], v[196:199], v[44:47]
	v_mfma_f32_16x16x32_bf16 v[40:43], v[164:167], v[196:199], v[40:43]
	v_mfma_f32_16x16x32_bf16 v[28:31], v[156:159], v[204:207], v[28:31]
	v_mfma_f32_16x16x32_bf16 v[24:27], v[164:167], v[204:207], v[24:27]
	v_mfma_f32_16x16x32_bf16 v[12:15], v[156:159], v[212:215], v[12:15]
	v_mfma_f32_16x16x32_bf16 v[8:11], v[164:167], v[212:215], v[8:11]
	v_mfma_f32_16x16x32_bf16 v[52:55], v[168:171], v[184:187], v[52:55]
	v_mfma_f32_16x16x32_bf16 v[48:51], v[176:179], v[184:187], v[48:51]
	v_mfma_f32_16x16x32_bf16 v[36:39], v[168:171], v[192:195], v[36:39]
	v_mfma_f32_16x16x32_bf16 v[32:35], v[176:179], v[192:195], v[32:35]
	v_mfma_f32_16x16x32_bf16 v[20:23], v[168:171], v[200:203], v[20:23]
	v_mfma_f32_16x16x32_bf16 v[16:19], v[176:179], v[200:203], v[16:19]
	v_mfma_f32_16x16x32_bf16 v[4:7], v[168:171], v[208:211], v[4:7]
	v_mfma_f32_16x16x32_bf16 v[0:3], v[176:179], v[208:211], v[0:3]
	v_mfma_f32_16x16x32_bf16 v[52:55], v[172:175], v[188:191], v[52:55]
	v_mfma_f32_16x16x32_bf16 v[48:51], v[180:183], v[188:191], v[48:51]
	v_mfma_f32_16x16x32_bf16 v[36:39], v[172:175], v[196:199], v[36:39]
	v_mfma_f32_16x16x32_bf16 v[32:35], v[180:183], v[196:199], v[32:35]
	v_mfma_f32_16x16x32_bf16 v[20:23], v[172:175], v[204:207], v[20:23]
	v_mfma_f32_16x16x32_bf16 v[16:19], v[180:183], v[204:207], v[16:19]
	v_mfma_f32_16x16x32_bf16 v[4:7], v[172:175], v[212:215], v[4:7]
	v_mfma_f32_16x16x32_bf16 v[0:3], v[180:183], v[212:215], v[0:3]
	s_setprio 0
	s_barrier
	s_add_i32 s55, s55, 2
	s_add_u32 s24, s24, 0x100
	s_addc_u32 s25, s25, 0
	s_add_u32 s53, s53, 0x100
	s_addc_u32 s54, s54, 0
	s_cmp_gt_u32 s55, 41
	s_cbranch_scc0 .LBB0_2734
	s_and_b64 vcc, exec, s[20:21]
	s_cbranch_vccz .LBB0_2737
	s_barrier
